# v41 + s_setprio removed from the five GEMM K-loops
# speedup vs baseline: 1.0246x; 1.0039x over previous
.LBB0_142:
	s_add_u32 s18, s16, 0xfffc0080
	s_addc_u32 s19, s17, -1
	s_add_i32 s28, 0, 0x10000
	s_cmp_eq_u32 s88, 12
	s_cselect_b32 s53, s47, s19
	s_cselect_b32 s52, s78, s18
	v_add_u32_e32 v140, s28, v143
	s_cselect_b32 s19, s15, s85
	s_cselect_b32 s18, s79, s83
	s_add_i32 s29, 0, 0x14000
	ds_read_b128 v[146:149], v140
	ds_read_b128 v[150:153], v140 offset:1024
	ds_read_b128 v[154:157], v140 offset:2048
	ds_read_b128 v[158:161], v140 offset:3072
	v_add_u32_e32 v140, s29, v143
	ds_read_b128 v[162:165], v140
	ds_read_b128 v[166:169], v140 offset:1024
	ds_read_b128 v[174:177], v140 offset:2048
	ds_read_b128 v[178:181], v140 offset:3072
	v_lshl_add_u64 v[140:141], s[16:17], 0, v[136:137]
	s_add_i32 m0, s54, 0xc000
	ds_read_b128 v[182:185], v145
	ds_read_b128 v[186:189], v145 offset:1024
	ds_read_b128 v[190:193], v145 offset:2048
	ds_read_b128 v[194:197], v145 offset:3072
	ds_read_b128 v[198:201], v145 offset:4096
	ds_read_b128 v[202:205], v145 offset:5120
	ds_read_b128 v[236:239], v145 offset:6144
	ds_read_b128 v[240:243], v145 offset:7168
	global_load_lds_dwordx4 v[140:141], off
	v_lshl_add_u64 v[140:141], s[16:17], 0, v[138:139]
	s_add_i32 m0, s54, 0xe000
	s_nop 0
	global_load_lds_dwordx4 v[140:141], off
	s_waitcnt vmcnt(8)
	s_waitcnt lgkmcnt(0)
	s_barrier
	s_waitcnt lgkmcnt(0)
	v_mfma_f32_16x16x32_bf16 v[126:129], v[146:149], v[182:185], v[126:129]
	v_mfma_f32_16x16x32_bf16 v[118:121], v[154:157], v[182:185], v[118:121]
	v_mfma_f32_16x16x32_bf16 v[110:113], v[146:149], v[190:193], v[110:113]
	v_mfma_f32_16x16x32_bf16 v[102:105], v[154:157], v[190:193], v[102:105]
	v_mfma_f32_16x16x32_bf16 v[94:97], v[146:149], v[198:201], v[94:97]
	v_mfma_f32_16x16x32_bf16 v[86:89], v[154:157], v[198:201], v[86:89]
	v_mfma_f32_16x16x32_bf16 v[78:81], v[146:149], v[236:239], v[78:81]
	v_mfma_f32_16x16x32_bf16 v[70:73], v[154:157], v[236:239], v[70:73]
	v_mfma_f32_16x16x32_bf16 v[126:129], v[150:153], v[186:189], v[126:129]
	v_mfma_f32_16x16x32_bf16 v[118:121], v[158:161], v[186:189], v[118:121]
	v_mfma_f32_16x16x32_bf16 v[110:113], v[150:153], v[194:197], v[110:113]
	v_mfma_f32_16x16x32_bf16 v[102:105], v[158:161], v[194:197], v[102:105]
	v_mfma_f32_16x16x32_bf16 v[94:97], v[150:153], v[202:205], v[94:97]
	v_mfma_f32_16x16x32_bf16 v[86:89], v[158:161], v[202:205], v[86:89]
	v_mfma_f32_16x16x32_bf16 v[78:81], v[150:153], v[240:243], v[78:81]
	v_mfma_f32_16x16x32_bf16 v[70:73], v[158:161], v[240:243], v[70:73]
	v_mfma_f32_16x16x32_bf16 v[122:125], v[162:165], v[182:185], v[122:125]
	v_mfma_f32_16x16x32_bf16 v[114:117], v[174:177], v[182:185], v[114:117]
	v_mfma_f32_16x16x32_bf16 v[106:109], v[162:165], v[190:193], v[106:109]
	v_mfma_f32_16x16x32_bf16 v[98:101], v[174:177], v[190:193], v[98:101]
	v_mfma_f32_16x16x32_bf16 v[90:93], v[162:165], v[198:201], v[90:93]
	v_mfma_f32_16x16x32_bf16 v[82:85], v[174:177], v[198:201], v[82:85]
	v_mfma_f32_16x16x32_bf16 v[74:77], v[162:165], v[236:239], v[74:77]
	v_mfma_f32_16x16x32_bf16 v[66:69], v[174:177], v[236:239], v[66:69]
	v_mfma_f32_16x16x32_bf16 v[122:125], v[166:169], v[186:189], v[122:125]
	v_mfma_f32_16x16x32_bf16 v[114:117], v[178:181], v[186:189], v[114:117]
	v_mfma_f32_16x16x32_bf16 v[106:109], v[166:169], v[194:197], v[106:109]
	v_mfma_f32_16x16x32_bf16 v[98:101], v[178:181], v[194:197], v[98:101]
	v_mfma_f32_16x16x32_bf16 v[90:93], v[166:169], v[202:205], v[90:93]
	v_mfma_f32_16x16x32_bf16 v[82:85], v[178:181], v[202:205], v[82:85]
	v_mfma_f32_16x16x32_bf16 v[74:77], v[166:169], v[240:243], v[74:77]
	v_mfma_f32_16x16x32_bf16 v[66:69], v[178:181], v[240:243], v[66:69]
	s_barrier
	s_add_i32 s28, s28, s41
	v_lshl_add_u64 v[140:141], s[18:19], 0, v[0:1]
	s_mov_b32 m0, s28
	ds_read_b128 v[182:185], v145 offset:16384
	ds_read_b128 v[186:189], v145 offset:17408
	ds_read_b128 v[190:193], v145 offset:18432
	ds_read_b128 v[194:197], v145 offset:19456
	ds_read_b128 v[198:201], v145 offset:20480
	ds_read_b128 v[202:205], v145 offset:21504
	ds_read_b128 v[236:239], v145 offset:22528
	ds_read_b128 v[240:243], v145 offset:23552
	global_load_lds_dwordx4 v[140:141], off
	s_add_i32 m0, s28, 0x2000
	s_add_u32 s36, s18, 0x40000
	v_lshl_add_u64 v[206:207], s[18:19], 0, v[130:131]
	s_addc_u32 s37, s19, 0
	s_add_i32 s28, s29, s41
	global_load_lds_dwordx4 v[206:207], off
	v_lshl_add_u64 v[228:229], s[36:37], 0, v[0:1]
	s_mov_b32 m0, s28
	v_lshl_add_u64 v[244:245], s[52:53], 0, v[132:133]
	global_load_lds_dwordx4 v[228:229], off
	v_lshl_add_u64 v[228:229], s[36:37], 0, v[130:131]
	s_add_i32 m0, s28, 0x2000
	s_nop 0
	global_load_lds_dwordx4 v[228:229], off
	v_lshl_add_u64 v[228:229], s[52:53], 0, v[134:135]
	s_mov_b32 m0, s54
	s_nop 0
	global_load_lds_dwordx4 v[228:229], off
	s_mov_b32 m0, s55
	s_nop 0
	global_load_lds_dwordx4 v[244:245], off
	s_waitcnt vmcnt(8)
	s_waitcnt lgkmcnt(0)
	s_barrier
	s_waitcnt lgkmcnt(0)
	v_mfma_f32_16x16x32_bf16 v[62:65], v[146:149], v[182:185], v[62:65]
	v_mfma_f32_16x16x32_bf16 v[54:57], v[154:157], v[182:185], v[54:57]
	v_mfma_f32_16x16x32_bf16 v[46:49], v[146:149], v[190:193], v[46:49]
	v_mfma_f32_16x16x32_bf16 v[38:41], v[154:157], v[190:193], v[38:41]
	v_mfma_f32_16x16x32_bf16 v[30:33], v[146:149], v[198:201], v[30:33]
	v_mfma_f32_16x16x32_bf16 v[22:25], v[154:157], v[198:201], v[22:25]
	v_mfma_f32_16x16x32_bf16 v[14:17], v[146:149], v[236:239], v[14:17]
	v_mfma_f32_16x16x32_bf16 v[6:9], v[154:157], v[236:239], v[6:9]
	v_mfma_f32_16x16x32_bf16 v[62:65], v[150:153], v[186:189], v[62:65]
	v_mfma_f32_16x16x32_bf16 v[54:57], v[158:161], v[186:189], v[54:57]
	v_mfma_f32_16x16x32_bf16 v[46:49], v[150:153], v[194:197], v[46:49]
	v_mfma_f32_16x16x32_bf16 v[38:41], v[158:161], v[194:197], v[38:41]
	v_mfma_f32_16x16x32_bf16 v[30:33], v[150:153], v[202:205], v[30:33]
	v_mfma_f32_16x16x32_bf16 v[22:25], v[158:161], v[202:205], v[22:25]
	v_mfma_f32_16x16x32_bf16 v[14:17], v[150:153], v[240:243], v[14:17]
	v_mfma_f32_16x16x32_bf16 v[6:9], v[158:161], v[240:243], v[6:9]
	v_mfma_f32_16x16x32_bf16 v[58:61], v[162:165], v[182:185], v[58:61]
	v_mfma_f32_16x16x32_bf16 v[50:53], v[174:177], v[182:185], v[50:53]
	v_mfma_f32_16x16x32_bf16 v[42:45], v[162:165], v[190:193], v[42:45]
	v_mfma_f32_16x16x32_bf16 v[34:37], v[174:177], v[190:193], v[34:37]
	v_mfma_f32_16x16x32_bf16 v[26:29], v[162:165], v[198:201], v[26:29]
	v_mfma_f32_16x16x32_bf16 v[18:21], v[174:177], v[198:201], v[18:21]
	v_mfma_f32_16x16x32_bf16 v[10:13], v[162:165], v[236:239], v[10:13]
	v_mfma_f32_16x16x32_bf16 v[2:5], v[174:177], v[236:239], v[2:5]
	v_mfma_f32_16x16x32_bf16 v[58:61], v[166:169], v[186:189], v[58:61]
	v_mfma_f32_16x16x32_bf16 v[50:53], v[178:181], v[186:189], v[50:53]
	v_mfma_f32_16x16x32_bf16 v[42:45], v[166:169], v[194:197], v[42:45]
	v_mfma_f32_16x16x32_bf16 v[34:37], v[178:181], v[194:197], v[34:37]
	v_mfma_f32_16x16x32_bf16 v[26:29], v[166:169], v[202:205], v[26:29]
	v_mfma_f32_16x16x32_bf16 v[18:21], v[178:181], v[202:205], v[18:21]
	v_mfma_f32_16x16x32_bf16 v[10:13], v[166:169], v[240:243], v[10:13]
	v_mfma_f32_16x16x32_bf16 v[2:5], v[178:181], v[240:243], v[2:5]
	s_barrier
	s_add_i32 s28, 0, 0x18000
	s_add_i32 s29, 0, 0x1c000
	v_add_u32_e32 v158, s28, v143
	v_add_u32_e32 v178, s29, v143
	ds_read_b128 v[146:149], v158
	ds_read_b128 v[150:153], v158 offset:1024
	ds_read_b128 v[154:157], v158 offset:2048
	ds_read_b128 v[158:161], v158 offset:3072
	ds_read_b128 v[162:165], v178
	ds_read_b128 v[166:169], v178 offset:1024
	ds_read_b128 v[174:177], v178 offset:2048
	ds_read_b128 v[178:181], v178 offset:3072
	s_add_u32 s36, s52, 0x40000
	s_addc_u32 s37, s53, 0
	s_mov_b32 m0, s70
	v_lshl_add_u64 v[246:247], s[36:37], 0, v[134:135]
	ds_read_b128 v[182:185], v145 offset:32768
	ds_read_b128 v[186:189], v145 offset:33792
	ds_read_b128 v[190:193], v145 offset:34816
	ds_read_b128 v[194:197], v145 offset:35840
	ds_read_b128 v[198:201], v145 offset:36864
	ds_read_b128 v[202:205], v145 offset:37888
	ds_read_b128 v[236:239], v145 offset:38912
	ds_read_b128 v[240:243], v145 offset:39936
	global_load_lds_dwordx4 v[246:247], off
	v_lshl_add_u64 v[246:247], s[36:37], 0, v[132:133]
	s_mov_b32 m0, s71
	s_nop 0
	global_load_lds_dwordx4 v[246:247], off
	s_waitcnt vmcnt(8)
	s_waitcnt lgkmcnt(0)
	s_barrier
	s_waitcnt lgkmcnt(0)
	v_mfma_f32_16x16x32_bf16 v[126:129], v[146:149], v[182:185], v[126:129]
	v_mfma_f32_16x16x32_bf16 v[118:121], v[154:157], v[182:185], v[118:121]
	v_mfma_f32_16x16x32_bf16 v[110:113], v[146:149], v[190:193], v[110:113]
	v_mfma_f32_16x16x32_bf16 v[102:105], v[154:157], v[190:193], v[102:105]
	v_mfma_f32_16x16x32_bf16 v[94:97], v[146:149], v[198:201], v[94:97]
	v_mfma_f32_16x16x32_bf16 v[86:89], v[154:157], v[198:201], v[86:89]
	v_mfma_f32_16x16x32_bf16 v[78:81], v[146:149], v[236:239], v[78:81]
	v_mfma_f32_16x16x32_bf16 v[70:73], v[154:157], v[236:239], v[70:73]
	v_mfma_f32_16x16x32_bf16 v[126:129], v[150:153], v[186:189], v[126:129]
	v_mfma_f32_16x16x32_bf16 v[118:121], v[158:161], v[186:189], v[118:121]
	v_mfma_f32_16x16x32_bf16 v[110:113], v[150:153], v[194:197], v[110:113]
	v_mfma_f32_16x16x32_bf16 v[102:105], v[158:161], v[194:197], v[102:105]
	v_mfma_f32_16x16x32_bf16 v[94:97], v[150:153], v[202:205], v[94:97]
	v_mfma_f32_16x16x32_bf16 v[86:89], v[158:161], v[202:205], v[86:89]
	v_mfma_f32_16x16x32_bf16 v[78:81], v[150:153], v[240:243], v[78:81]
	v_mfma_f32_16x16x32_bf16 v[70:73], v[158:161], v[240:243], v[70:73]
	v_mfma_f32_16x16x32_bf16 v[122:125], v[162:165], v[182:185], v[122:125]
	v_mfma_f32_16x16x32_bf16 v[114:117], v[174:177], v[182:185], v[114:117]
	v_mfma_f32_16x16x32_bf16 v[106:109], v[162:165], v[190:193], v[106:109]
	v_mfma_f32_16x16x32_bf16 v[98:101], v[174:177], v[190:193], v[98:101]
	v_mfma_f32_16x16x32_bf16 v[90:93], v[162:165], v[198:201], v[90:93]
	v_mfma_f32_16x16x32_bf16 v[82:85], v[174:177], v[198:201], v[82:85]
	v_mfma_f32_16x16x32_bf16 v[74:77], v[162:165], v[236:239], v[74:77]
	v_mfma_f32_16x16x32_bf16 v[66:69], v[174:177], v[236:239], v[66:69]
	v_mfma_f32_16x16x32_bf16 v[122:125], v[166:169], v[186:189], v[122:125]
	v_mfma_f32_16x16x32_bf16 v[114:117], v[178:181], v[186:189], v[114:117]
	v_mfma_f32_16x16x32_bf16 v[106:109], v[166:169], v[194:197], v[106:109]
	v_mfma_f32_16x16x32_bf16 v[98:101], v[178:181], v[194:197], v[98:101]
	v_mfma_f32_16x16x32_bf16 v[90:93], v[166:169], v[202:205], v[90:93]
	v_mfma_f32_16x16x32_bf16 v[82:85], v[178:181], v[202:205], v[82:85]
	v_mfma_f32_16x16x32_bf16 v[74:77], v[166:169], v[240:243], v[74:77]
	v_mfma_f32_16x16x32_bf16 v[66:69], v[178:181], v[240:243], v[66:69]
	s_barrier
	s_add_i32 s28, s28, s41
	v_lshl_add_u64 v[140:141], v[140:141], 0, s[4:5]
	s_mov_b32 m0, s28
	ds_read_b128 v[182:185], v145 offset:49152
	ds_read_b128 v[186:189], v145 offset:50176
	ds_read_b128 v[190:193], v145 offset:51200
	ds_read_b128 v[194:197], v145 offset:52224
	ds_read_b128 v[198:201], v145 offset:53248
	ds_read_b128 v[202:205], v145 offset:54272
	ds_read_b128 v[236:239], v145 offset:55296
	ds_read_b128 v[240:243], v145 offset:56320
	global_load_lds_dwordx4 v[140:141], off
	s_add_i32 m0, s28, 0x2000
	s_add_u32 s18, s18, 0x40080
	v_lshl_add_u64 v[140:141], v[206:207], 0, s[4:5]
	s_addc_u32 s19, s19, 0
	s_add_i32 s28, s29, s41
	global_load_lds_dwordx4 v[140:141], off
	v_lshl_add_u64 v[140:141], s[18:19], 0, v[0:1]
	s_mov_b32 m0, s28
	s_nop 0
	global_load_lds_dwordx4 v[140:141], off
	v_lshl_add_u64 v[140:141], s[18:19], 0, v[130:131]
	s_add_i32 m0, s28, 0x2000
	s_nop 0
	global_load_lds_dwordx4 v[140:141], off
	v_lshl_add_u64 v[140:141], v[228:229], 0, s[4:5]
	s_mov_b32 m0, s74
	s_nop 0
	global_load_lds_dwordx4 v[140:141], off
	v_lshl_add_u64 v[140:141], v[244:245], 0, s[4:5]
	s_mov_b32 m0, s75
	s_nop 0
	global_load_lds_dwordx4 v[140:141], off
	s_waitcnt vmcnt(8)
	s_waitcnt lgkmcnt(0)
	s_barrier
	s_waitcnt lgkmcnt(0)
	v_mfma_f32_16x16x32_bf16 v[62:65], v[146:149], v[182:185], v[62:65]
	v_mfma_f32_16x16x32_bf16 v[54:57], v[154:157], v[182:185], v[54:57]
	v_mfma_f32_16x16x32_bf16 v[46:49], v[146:149], v[190:193], v[46:49]
	v_mfma_f32_16x16x32_bf16 v[38:41], v[154:157], v[190:193], v[38:41]
	v_mfma_f32_16x16x32_bf16 v[30:33], v[146:149], v[198:201], v[30:33]
	v_mfma_f32_16x16x32_bf16 v[22:25], v[154:157], v[198:201], v[22:25]
	v_mfma_f32_16x16x32_bf16 v[14:17], v[146:149], v[236:239], v[14:17]
	v_mfma_f32_16x16x32_bf16 v[6:9], v[154:157], v[236:239], v[6:9]
	v_mfma_f32_16x16x32_bf16 v[62:65], v[150:153], v[186:189], v[62:65]
	v_mfma_f32_16x16x32_bf16 v[54:57], v[158:161], v[186:189], v[54:57]
	v_mfma_f32_16x16x32_bf16 v[46:49], v[150:153], v[194:197], v[46:49]
	v_mfma_f32_16x16x32_bf16 v[38:41], v[158:161], v[194:197], v[38:41]
	v_mfma_f32_16x16x32_bf16 v[30:33], v[150:153], v[202:205], v[30:33]
	v_mfma_f32_16x16x32_bf16 v[22:25], v[158:161], v[202:205], v[22:25]
	v_mfma_f32_16x16x32_bf16 v[14:17], v[150:153], v[240:243], v[14:17]
	v_mfma_f32_16x16x32_bf16 v[6:9], v[158:161], v[240:243], v[6:9]
	v_mfma_f32_16x16x32_bf16 v[58:61], v[162:165], v[182:185], v[58:61]
	v_mfma_f32_16x16x32_bf16 v[50:53], v[174:177], v[182:185], v[50:53]
	v_mfma_f32_16x16x32_bf16 v[42:45], v[162:165], v[190:193], v[42:45]
	v_mfma_f32_16x16x32_bf16 v[34:37], v[174:177], v[190:193], v[34:37]
	v_mfma_f32_16x16x32_bf16 v[26:29], v[162:165], v[198:201], v[26:29]
	v_mfma_f32_16x16x32_bf16 v[18:21], v[174:177], v[198:201], v[18:21]
	v_mfma_f32_16x16x32_bf16 v[10:13], v[162:165], v[236:239], v[10:13]
	v_mfma_f32_16x16x32_bf16 v[2:5], v[174:177], v[236:239], v[2:5]
	v_mfma_f32_16x16x32_bf16 v[58:61], v[166:169], v[186:189], v[58:61]
	v_mfma_f32_16x16x32_bf16 v[50:53], v[178:181], v[186:189], v[50:53]
	v_mfma_f32_16x16x32_bf16 v[42:45], v[166:169], v[194:197], v[42:45]
	v_mfma_f32_16x16x32_bf16 v[34:37], v[178:181], v[194:197], v[34:37]
	v_mfma_f32_16x16x32_bf16 v[26:29], v[166:169], v[202:205], v[26:29]
	v_mfma_f32_16x16x32_bf16 v[18:21], v[178:181], v[202:205], v[18:21]
	v_mfma_f32_16x16x32_bf16 v[10:13], v[166:169], v[240:243], v[10:13]
	v_mfma_f32_16x16x32_bf16 v[2:5], v[178:181], v[240:243], v[2:5]
	s_barrier
	s_add_i32 s88, s88, 2
	s_add_u32 s16, s16, 0x100
	s_addc_u32 s17, s17, 0
	s_add_u32 s83, s83, 0x100
	s_addc_u32 s85, s85, 0
	s_cmp_gt_u32 s88, 13
	s_cbranch_scc0 .LBB0_142
	s_and_b64 vcc, exec, s[12:13]
	s_cbranch_vccz .LBB0_145
	s_barrier

.LBB0_194:
	s_add_i32 vcc_lo, s12, 2
	s_add_u32 s36, s10, 0x80
	s_addc_u32 s13, s11, 0
	s_add_i32 vcc_hi, 0, 0x10000
	s_cmp_eq_u32 s94, s12
	s_cselect_b32 s13, s45, s13
	s_cselect_b32 s12, s44, s36
	s_cselect_b32 s37, s79, s15
	s_cselect_b32 s36, s78, s14
	s_add_i32 s8, 0, 0x14000
	v_add_u32_e32 v126, vcc_hi, v197
	v_add_u32_e32 v158, s8, v197
	ds_read_b128 v[114:117], v126
	ds_read_b128 v[118:121], v126 offset:1024
	ds_read_b128 v[122:125], v126 offset:2048
	ds_read_b128 v[126:129], v126 offset:3072
	ds_read_b128 v[146:149], v158
	ds_read_b128 v[150:153], v158 offset:1024
	ds_read_b128 v[154:157], v158 offset:2048
	ds_read_b128 v[158:161], v158 offset:3072
	v_lshl_add_u64 v[240:241], s[10:11], 0, v[180:181]
	s_add_i32 m0, s18, 0xc000
	ds_read_b128 v[162:165], v199
	ds_read_b128 v[166:169], v199 offset:1024
	ds_read_b128 v[184:187], v199 offset:2048
	ds_read_b128 v[188:191], v199 offset:3072
	ds_read_b128 v[192:195], v199 offset:4096
	ds_read_b128 v[200:203], v199 offset:5120
	ds_read_b128 v[204:207], v199 offset:6144
	ds_read_b128 v[236:239], v199 offset:7168
	global_load_lds_dwordx4 v[240:241], off
	v_lshl_add_u64 v[240:241], s[10:11], 0, v[182:183]
	s_add_i32 m0, s18, 0xe000
	s_nop 0
	global_load_lds_dwordx4 v[240:241], off
	s_waitcnt vmcnt(8)
	s_waitcnt lgkmcnt(0)
	s_barrier
	s_waitcnt lgkmcnt(0)
	v_mfma_f32_16x16x32_bf16 v[142:145], v[114:117], v[162:165], v[142:145]
	v_mfma_f32_16x16x32_bf16 v[138:141], v[122:125], v[162:165], v[138:141]
	v_mfma_f32_16x16x32_bf16 v[110:113], v[114:117], v[184:187], v[110:113]
	v_mfma_f32_16x16x32_bf16 v[106:109], v[122:125], v[184:187], v[106:109]
	v_mfma_f32_16x16x32_bf16 v[94:97], v[114:117], v[192:195], v[94:97]
	v_mfma_f32_16x16x32_bf16 v[90:93], v[122:125], v[192:195], v[90:93]
	v_mfma_f32_16x16x32_bf16 v[78:81], v[114:117], v[204:207], v[78:81]
	v_mfma_f32_16x16x32_bf16 v[74:77], v[122:125], v[204:207], v[74:77]
	v_mfma_f32_16x16x32_bf16 v[142:145], v[118:121], v[166:169], v[142:145]
	v_mfma_f32_16x16x32_bf16 v[138:141], v[126:129], v[166:169], v[138:141]
	v_mfma_f32_16x16x32_bf16 v[110:113], v[118:121], v[188:191], v[110:113]
	v_mfma_f32_16x16x32_bf16 v[106:109], v[126:129], v[188:191], v[106:109]
	v_mfma_f32_16x16x32_bf16 v[94:97], v[118:121], v[200:203], v[94:97]
	v_mfma_f32_16x16x32_bf16 v[90:93], v[126:129], v[200:203], v[90:93]
	v_mfma_f32_16x16x32_bf16 v[78:81], v[118:121], v[236:239], v[78:81]
	v_mfma_f32_16x16x32_bf16 v[74:77], v[126:129], v[236:239], v[74:77]
	v_mfma_f32_16x16x32_bf16 v[134:137], v[146:149], v[162:165], v[134:137]
	v_mfma_f32_16x16x32_bf16 v[130:133], v[154:157], v[162:165], v[130:133]
	v_mfma_f32_16x16x32_bf16 v[102:105], v[146:149], v[184:187], v[102:105]
	v_mfma_f32_16x16x32_bf16 v[98:101], v[154:157], v[184:187], v[98:101]
	v_mfma_f32_16x16x32_bf16 v[86:89], v[146:149], v[192:195], v[86:89]
	v_mfma_f32_16x16x32_bf16 v[82:85], v[154:157], v[192:195], v[82:85]
	v_mfma_f32_16x16x32_bf16 v[70:73], v[146:149], v[204:207], v[70:73]
	v_mfma_f32_16x16x32_bf16 v[66:69], v[154:157], v[204:207], v[66:69]
	v_mfma_f32_16x16x32_bf16 v[134:137], v[150:153], v[166:169], v[134:137]
	v_mfma_f32_16x16x32_bf16 v[130:133], v[158:161], v[166:169], v[130:133]
	v_mfma_f32_16x16x32_bf16 v[102:105], v[150:153], v[188:191], v[102:105]
	v_mfma_f32_16x16x32_bf16 v[98:101], v[158:161], v[188:191], v[98:101]
	v_mfma_f32_16x16x32_bf16 v[86:89], v[150:153], v[200:203], v[86:89]
	v_mfma_f32_16x16x32_bf16 v[82:85], v[158:161], v[200:203], v[82:85]
	v_mfma_f32_16x16x32_bf16 v[70:73], v[150:153], v[236:239], v[70:73]
	v_mfma_f32_16x16x32_bf16 v[66:69], v[158:161], v[236:239], v[66:69]
	s_barrier
	s_add_i32 s9, vcc_hi, s17
	v_lshl_add_u64 v[240:241], s[36:37], 0, v[0:1]
	s_mov_b32 m0, s9
	ds_read_b128 v[162:165], v199 offset:16384
	ds_read_b128 v[166:169], v199 offset:17408
	ds_read_b128 v[184:187], v199 offset:18432
	ds_read_b128 v[188:191], v199 offset:19456
	ds_read_b128 v[192:195], v199 offset:20480
	ds_read_b128 v[200:203], v199 offset:21504
	ds_read_b128 v[204:207], v199 offset:22528
	ds_read_b128 v[236:239], v199 offset:23552
	global_load_lds_dwordx4 v[240:241], off
	s_add_i32 m0, s9, 0x2000
	v_lshl_add_u64 v[242:243], s[36:37], 0, v[174:175]
	s_add_u32 s36, s36, s20
	s_addc_u32 s37, s37, 0
	s_add_i32 s8, s8, s17
	global_load_lds_dwordx4 v[242:243], off
	v_lshl_add_u64 v[244:245], s[36:37], 0, v[0:1]
	s_mov_b32 m0, s8
	v_lshl_add_u64 v[246:247], s[36:37], 0, v[174:175]
	global_load_lds_dwordx4 v[244:245], off
	s_add_i32 m0, s8, 0x2000
	v_lshl_add_u64 v[248:249], s[12:13], 0, v[178:179]
	global_load_lds_dwordx4 v[246:247], off
	s_mov_b32 m0, s18
	v_lshl_add_u64 v[250:251], s[12:13], 0, v[176:177]
	global_load_lds_dwordx4 v[248:249], off
	s_mov_b32 m0, s19
	s_nop 0
	global_load_lds_dwordx4 v[250:251], off
	s_waitcnt vmcnt(8)
	s_waitcnt lgkmcnt(0)
	s_barrier
	s_waitcnt lgkmcnt(0)
	v_mfma_f32_16x16x32_bf16 v[62:65], v[114:117], v[162:165], v[62:65]
	v_mfma_f32_16x16x32_bf16 v[58:61], v[122:125], v[162:165], v[58:61]
	v_mfma_f32_16x16x32_bf16 v[46:49], v[114:117], v[184:187], v[46:49]
	v_mfma_f32_16x16x32_bf16 v[42:45], v[122:125], v[184:187], v[42:45]
	v_mfma_f32_16x16x32_bf16 v[30:33], v[114:117], v[192:195], v[30:33]
	v_mfma_f32_16x16x32_bf16 v[26:29], v[122:125], v[192:195], v[26:29]
	v_mfma_f32_16x16x32_bf16 v[14:17], v[114:117], v[204:207], v[14:17]
	v_mfma_f32_16x16x32_bf16 v[10:13], v[122:125], v[204:207], v[10:13]
	v_mfma_f32_16x16x32_bf16 v[62:65], v[118:121], v[166:169], v[62:65]
	v_mfma_f32_16x16x32_bf16 v[58:61], v[126:129], v[166:169], v[58:61]
	v_mfma_f32_16x16x32_bf16 v[46:49], v[118:121], v[188:191], v[46:49]
	v_mfma_f32_16x16x32_bf16 v[42:45], v[126:129], v[188:191], v[42:45]
	v_mfma_f32_16x16x32_bf16 v[30:33], v[118:121], v[200:203], v[30:33]
	v_mfma_f32_16x16x32_bf16 v[26:29], v[126:129], v[200:203], v[26:29]
	v_mfma_f32_16x16x32_bf16 v[14:17], v[118:121], v[236:239], v[14:17]
	v_mfma_f32_16x16x32_bf16 v[10:13], v[126:129], v[236:239], v[10:13]
	v_mfma_f32_16x16x32_bf16 v[54:57], v[146:149], v[162:165], v[54:57]
	v_mfma_f32_16x16x32_bf16 v[50:53], v[154:157], v[162:165], v[50:53]
	v_mfma_f32_16x16x32_bf16 v[38:41], v[146:149], v[184:187], v[38:41]
	v_mfma_f32_16x16x32_bf16 v[34:37], v[154:157], v[184:187], v[34:37]
	v_mfma_f32_16x16x32_bf16 v[22:25], v[146:149], v[192:195], v[22:25]
	v_mfma_f32_16x16x32_bf16 v[18:21], v[154:157], v[192:195], v[18:21]
	v_mfma_f32_16x16x32_bf16 v[6:9], v[146:149], v[204:207], v[6:9]
	v_mfma_f32_16x16x32_bf16 v[2:5], v[154:157], v[204:207], v[2:5]
	v_mfma_f32_16x16x32_bf16 v[54:57], v[150:153], v[166:169], v[54:57]
	v_mfma_f32_16x16x32_bf16 v[50:53], v[158:161], v[166:169], v[50:53]
	v_mfma_f32_16x16x32_bf16 v[38:41], v[150:153], v[188:191], v[38:41]
	v_mfma_f32_16x16x32_bf16 v[34:37], v[158:161], v[188:191], v[34:37]
	v_mfma_f32_16x16x32_bf16 v[22:25], v[150:153], v[200:203], v[22:25]
	v_mfma_f32_16x16x32_bf16 v[18:21], v[158:161], v[200:203], v[18:21]
	v_mfma_f32_16x16x32_bf16 v[6:9], v[150:153], v[236:239], v[6:9]
	v_mfma_f32_16x16x32_bf16 v[2:5], v[158:161], v[236:239], v[2:5]
	s_barrier
	s_add_i32 s8, 0, 0x18000
	s_add_i32 s9, 0, 0x1c000
	v_add_u32_e32 v126, s8, v197
	v_add_u32_e32 v158, s9, v197
	ds_read_b128 v[114:117], v126
	ds_read_b128 v[118:121], v126 offset:1024
	ds_read_b128 v[122:125], v126 offset:2048
	ds_read_b128 v[126:129], v126 offset:3072
	ds_read_b128 v[146:149], v158
	ds_read_b128 v[150:153], v158 offset:1024
	ds_read_b128 v[154:157], v158 offset:2048
	ds_read_b128 v[158:161], v158 offset:3072
	s_add_u32 s12, s12, s20
	s_addc_u32 s13, s13, 0
	s_mov_b32 m0, s70
	v_lshl_add_u64 v[228:229], s[12:13], 0, v[178:179]
	ds_read_b128 v[162:165], v199 offset:32768
	ds_read_b128 v[166:169], v199 offset:33792
	ds_read_b128 v[184:187], v199 offset:34816
	ds_read_b128 v[188:191], v199 offset:35840
	ds_read_b128 v[192:195], v199 offset:36864
	ds_read_b128 v[200:203], v199 offset:37888
	ds_read_b128 v[204:207], v199 offset:38912
	ds_read_b128 v[236:239], v199 offset:39936
	global_load_lds_dwordx4 v[228:229], off
	v_lshl_add_u64 v[228:229], s[12:13], 0, v[176:177]
	s_mov_b32 m0, s71
	s_nop 0
	global_load_lds_dwordx4 v[228:229], off
	s_waitcnt vmcnt(8)
	s_waitcnt lgkmcnt(0)
	s_barrier
	s_waitcnt lgkmcnt(0)
	v_mfma_f32_16x16x32_bf16 v[142:145], v[114:117], v[162:165], v[142:145]
	v_mfma_f32_16x16x32_bf16 v[138:141], v[122:125], v[162:165], v[138:141]
	v_mfma_f32_16x16x32_bf16 v[110:113], v[114:117], v[184:187], v[110:113]
	v_mfma_f32_16x16x32_bf16 v[106:109], v[122:125], v[184:187], v[106:109]
	v_mfma_f32_16x16x32_bf16 v[94:97], v[114:117], v[192:195], v[94:97]
	v_mfma_f32_16x16x32_bf16 v[90:93], v[122:125], v[192:195], v[90:93]
	v_mfma_f32_16x16x32_bf16 v[78:81], v[114:117], v[204:207], v[78:81]
	v_mfma_f32_16x16x32_bf16 v[74:77], v[122:125], v[204:207], v[74:77]
	v_mfma_f32_16x16x32_bf16 v[142:145], v[118:121], v[166:169], v[142:145]
	v_mfma_f32_16x16x32_bf16 v[138:141], v[126:129], v[166:169], v[138:141]
	v_mfma_f32_16x16x32_bf16 v[110:113], v[118:121], v[188:191], v[110:113]
	v_mfma_f32_16x16x32_bf16 v[106:109], v[126:129], v[188:191], v[106:109]
	v_mfma_f32_16x16x32_bf16 v[94:97], v[118:121], v[200:203], v[94:97]
	v_mfma_f32_16x16x32_bf16 v[90:93], v[126:129], v[200:203], v[90:93]
	v_mfma_f32_16x16x32_bf16 v[78:81], v[118:121], v[236:239], v[78:81]
	v_mfma_f32_16x16x32_bf16 v[74:77], v[126:129], v[236:239], v[74:77]
	v_mfma_f32_16x16x32_bf16 v[134:137], v[146:149], v[162:165], v[134:137]
	v_mfma_f32_16x16x32_bf16 v[130:133], v[154:157], v[162:165], v[130:133]
	v_mfma_f32_16x16x32_bf16 v[102:105], v[146:149], v[184:187], v[102:105]
	v_mfma_f32_16x16x32_bf16 v[98:101], v[154:157], v[184:187], v[98:101]
	v_mfma_f32_16x16x32_bf16 v[86:89], v[146:149], v[192:195], v[86:89]
	v_mfma_f32_16x16x32_bf16 v[82:85], v[154:157], v[192:195], v[82:85]
	v_mfma_f32_16x16x32_bf16 v[70:73], v[146:149], v[204:207], v[70:73]
	v_mfma_f32_16x16x32_bf16 v[66:69], v[154:157], v[204:207], v[66:69]
	v_mfma_f32_16x16x32_bf16 v[134:137], v[150:153], v[166:169], v[134:137]
	v_mfma_f32_16x16x32_bf16 v[130:133], v[158:161], v[166:169], v[130:133]
	v_mfma_f32_16x16x32_bf16 v[102:105], v[150:153], v[188:191], v[102:105]
	v_mfma_f32_16x16x32_bf16 v[98:101], v[158:161], v[188:191], v[98:101]
	v_mfma_f32_16x16x32_bf16 v[86:89], v[150:153], v[200:203], v[86:89]
	v_mfma_f32_16x16x32_bf16 v[82:85], v[158:161], v[200:203], v[82:85]
	v_mfma_f32_16x16x32_bf16 v[70:73], v[150:153], v[236:239], v[70:73]
	v_mfma_f32_16x16x32_bf16 v[66:69], v[158:161], v[236:239], v[66:69]
	s_barrier
	s_add_i32 s8, s8, s17
	v_lshl_add_u64 v[228:229], v[240:241], 0, s[4:5]
	s_mov_b32 m0, s8
	ds_read_b128 v[162:165], v199 offset:49152
	ds_read_b128 v[166:169], v199 offset:50176
	ds_read_b128 v[184:187], v199 offset:51200
	ds_read_b128 v[188:191], v199 offset:52224
	ds_read_b128 v[192:195], v199 offset:53248
	ds_read_b128 v[200:203], v199 offset:54272
	ds_read_b128 v[204:207], v199 offset:55296
	ds_read_b128 v[236:239], v199 offset:56320
	global_load_lds_dwordx4 v[228:229], off
	v_lshl_add_u64 v[228:229], v[242:243], 0, s[4:5]
	s_add_i32 m0, s8, 0x2000
	s_add_i32 s8, s9, s17
	global_load_lds_dwordx4 v[228:229], off
	v_lshl_add_u64 v[228:229], v[244:245], 0, s[4:5]
	s_mov_b32 m0, s8
	s_nop 0
	global_load_lds_dwordx4 v[228:229], off
	v_lshl_add_u64 v[228:229], v[246:247], 0, s[4:5]
	s_add_i32 m0, s8, 0x2000
	s_nop 0
	global_load_lds_dwordx4 v[228:229], off
	v_lshl_add_u64 v[228:229], v[248:249], 0, s[4:5]
	s_mov_b32 m0, s88
	s_nop 0
	global_load_lds_dwordx4 v[228:229], off
	v_lshl_add_u64 v[228:229], v[250:251], 0, s[4:5]
	s_mov_b32 m0, s89
	s_nop 0
	global_load_lds_dwordx4 v[228:229], off
	s_waitcnt vmcnt(8)
	s_waitcnt lgkmcnt(0)
	s_barrier
	s_waitcnt lgkmcnt(0)
	v_mfma_f32_16x16x32_bf16 v[62:65], v[114:117], v[162:165], v[62:65]
	v_mfma_f32_16x16x32_bf16 v[58:61], v[122:125], v[162:165], v[58:61]
	v_mfma_f32_16x16x32_bf16 v[46:49], v[114:117], v[184:187], v[46:49]
	v_mfma_f32_16x16x32_bf16 v[42:45], v[122:125], v[184:187], v[42:45]
	v_mfma_f32_16x16x32_bf16 v[30:33], v[114:117], v[192:195], v[30:33]
	v_mfma_f32_16x16x32_bf16 v[26:29], v[122:125], v[192:195], v[26:29]
	v_mfma_f32_16x16x32_bf16 v[14:17], v[114:117], v[204:207], v[14:17]
	v_mfma_f32_16x16x32_bf16 v[10:13], v[122:125], v[204:207], v[10:13]
	v_mfma_f32_16x16x32_bf16 v[62:65], v[118:121], v[166:169], v[62:65]
	v_mfma_f32_16x16x32_bf16 v[58:61], v[126:129], v[166:169], v[58:61]
	v_mfma_f32_16x16x32_bf16 v[46:49], v[118:121], v[188:191], v[46:49]
	v_mfma_f32_16x16x32_bf16 v[42:45], v[126:129], v[188:191], v[42:45]
	v_mfma_f32_16x16x32_bf16 v[30:33], v[118:121], v[200:203], v[30:33]
	v_mfma_f32_16x16x32_bf16 v[26:29], v[126:129], v[200:203], v[26:29]
	v_mfma_f32_16x16x32_bf16 v[14:17], v[118:121], v[236:239], v[14:17]
	v_mfma_f32_16x16x32_bf16 v[10:13], v[126:129], v[236:239], v[10:13]
	v_mfma_f32_16x16x32_bf16 v[54:57], v[146:149], v[162:165], v[54:57]
	v_mfma_f32_16x16x32_bf16 v[50:53], v[154:157], v[162:165], v[50:53]
	v_mfma_f32_16x16x32_bf16 v[38:41], v[146:149], v[184:187], v[38:41]
	v_mfma_f32_16x16x32_bf16 v[34:37], v[154:157], v[184:187], v[34:37]
	v_mfma_f32_16x16x32_bf16 v[22:25], v[146:149], v[192:195], v[22:25]
	v_mfma_f32_16x16x32_bf16 v[18:21], v[154:157], v[192:195], v[18:21]
	v_mfma_f32_16x16x32_bf16 v[6:9], v[146:149], v[204:207], v[6:9]
	v_mfma_f32_16x16x32_bf16 v[2:5], v[154:157], v[204:207], v[2:5]
	v_mfma_f32_16x16x32_bf16 v[54:57], v[150:153], v[166:169], v[54:57]
	v_mfma_f32_16x16x32_bf16 v[50:53], v[158:161], v[166:169], v[50:53]
	v_mfma_f32_16x16x32_bf16 v[38:41], v[150:153], v[188:191], v[38:41]
	v_mfma_f32_16x16x32_bf16 v[34:37], v[158:161], v[188:191], v[34:37]
	v_mfma_f32_16x16x32_bf16 v[22:25], v[150:153], v[200:203], v[22:25]
	v_mfma_f32_16x16x32_bf16 v[18:21], v[158:161], v[200:203], v[18:21]
	v_mfma_f32_16x16x32_bf16 v[6:9], v[150:153], v[236:239], v[6:9]
	v_mfma_f32_16x16x32_bf16 v[2:5], v[158:161], v[236:239], v[2:5]
	s_barrier
	s_add_u32 s10, s10, 0x100
	s_addc_u32 s11, s11, 0
	s_add_u32 s14, s14, 0x100
	s_addc_u32 s15, s15, 0
	s_cmp_ge_u32 vcc_lo, s77
	s_mov_b32 s12, vcc_lo
	s_cbranch_scc0 .LBB0_194
	s_and_b64 vcc, exec, s[54:55]
	s_cbranch_vccz .LBB0_197
	s_barrier

.LBB0_219:
	s_add_i32 vcc_lo, s48, 2
	s_add_u32 s36, s18, 0x80
	s_addc_u32 s37, s19, 0
	s_add_i32 vcc_hi, 0, 0x10000
	s_cmp_eq_u32 s89, s48
	s_cselect_b32 s49, s17, s37
	s_cselect_b32 s48, s16, s36
	s_cselect_b32 s37, s45, s15
	s_cselect_b32 s36, s44, s11
	s_add_i32 s28, 0, 0x14000
	v_add_u32_e32 v156, vcc_hi, v141
	v_add_u32_e32 v168, s28, v141
	ds_read_b128 v[144:147], v156
	ds_read_b128 v[148:151], v156 offset:1024
	ds_read_b128 v[152:155], v156 offset:2048
	ds_read_b128 v[156:159], v156 offset:3072
	ds_read_b128 v[160:163], v168
	ds_read_b128 v[164:167], v168 offset:1024
	ds_read_b128 v[174:177], v168 offset:2048
	ds_read_b128 v[178:181], v168 offset:3072
	v_lshl_add_u64 v[168:169], s[18:19], 0, v[136:137]
	s_add_i32 m0, s54, 0xc000
	ds_read_b128 v[182:185], v143
	ds_read_b128 v[186:189], v143 offset:1024
	ds_read_b128 v[190:193], v143 offset:2048
	ds_read_b128 v[194:197], v143 offset:3072
	ds_read_b128 v[198:201], v143 offset:4096
	ds_read_b128 v[202:205], v143 offset:5120
	ds_read_b128 v[236:239], v143 offset:6144
	ds_read_b128 v[240:243], v143 offset:7168
	global_load_lds_dwordx4 v[168:169], off
	v_lshl_add_u64 v[168:169], s[18:19], 0, v[138:139]
	s_add_i32 m0, s54, 0xe000
	s_nop 0
	global_load_lds_dwordx4 v[168:169], off
	s_waitcnt vmcnt(8)
	s_waitcnt lgkmcnt(0)
	s_barrier
	s_waitcnt lgkmcnt(0)
	v_mfma_f32_16x16x32_bf16 v[126:129], v[144:147], v[182:185], v[126:129]
	v_mfma_f32_16x16x32_bf16 v[122:125], v[152:155], v[182:185], v[122:125]
	v_mfma_f32_16x16x32_bf16 v[118:121], v[144:147], v[190:193], v[118:121]
	v_mfma_f32_16x16x32_bf16 v[114:117], v[152:155], v[190:193], v[114:117]
	v_mfma_f32_16x16x32_bf16 v[106:109], v[144:147], v[198:201], v[106:109]
	v_mfma_f32_16x16x32_bf16 v[98:101], v[152:155], v[198:201], v[98:101]
	v_mfma_f32_16x16x32_bf16 v[90:93], v[144:147], v[236:239], v[90:93]
	v_mfma_f32_16x16x32_bf16 v[82:85], v[152:155], v[236:239], v[82:85]
	v_mfma_f32_16x16x32_bf16 v[126:129], v[148:151], v[186:189], v[126:129]
	v_mfma_f32_16x16x32_bf16 v[122:125], v[156:159], v[186:189], v[122:125]
	v_mfma_f32_16x16x32_bf16 v[118:121], v[148:151], v[194:197], v[118:121]
	v_mfma_f32_16x16x32_bf16 v[114:117], v[156:159], v[194:197], v[114:117]
	v_mfma_f32_16x16x32_bf16 v[106:109], v[148:151], v[202:205], v[106:109]
	v_mfma_f32_16x16x32_bf16 v[98:101], v[156:159], v[202:205], v[98:101]
	v_mfma_f32_16x16x32_bf16 v[90:93], v[148:151], v[240:243], v[90:93]
	v_mfma_f32_16x16x32_bf16 v[82:85], v[156:159], v[240:243], v[82:85]
	v_mfma_f32_16x16x32_bf16 v[110:113], v[160:163], v[182:185], v[110:113]
	v_mfma_f32_16x16x32_bf16 v[102:105], v[174:177], v[182:185], v[102:105]
	v_mfma_f32_16x16x32_bf16 v[94:97], v[160:163], v[190:193], v[94:97]
	v_mfma_f32_16x16x32_bf16 v[86:89], v[174:177], v[190:193], v[86:89]
	v_mfma_f32_16x16x32_bf16 v[78:81], v[160:163], v[198:201], v[78:81]
	v_mfma_f32_16x16x32_bf16 v[74:77], v[174:177], v[198:201], v[74:77]
	v_mfma_f32_16x16x32_bf16 v[70:73], v[160:163], v[236:239], v[70:73]
	v_mfma_f32_16x16x32_bf16 v[66:69], v[174:177], v[236:239], v[66:69]
	v_mfma_f32_16x16x32_bf16 v[110:113], v[164:167], v[186:189], v[110:113]
	v_mfma_f32_16x16x32_bf16 v[102:105], v[178:181], v[186:189], v[102:105]
	v_mfma_f32_16x16x32_bf16 v[94:97], v[164:167], v[194:197], v[94:97]
	v_mfma_f32_16x16x32_bf16 v[86:89], v[178:181], v[194:197], v[86:89]
	v_mfma_f32_16x16x32_bf16 v[78:81], v[164:167], v[202:205], v[78:81]
	v_mfma_f32_16x16x32_bf16 v[74:77], v[178:181], v[202:205], v[74:77]
	v_mfma_f32_16x16x32_bf16 v[70:73], v[164:167], v[240:243], v[70:73]
	v_mfma_f32_16x16x32_bf16 v[66:69], v[178:181], v[240:243], v[66:69]
	s_barrier
	s_add_i32 s29, vcc_hi, s41
	v_lshl_add_u64 v[168:169], s[36:37], 0, v[0:1]
	s_mov_b32 m0, s29
	ds_read_b128 v[182:185], v143 offset:16384
	ds_read_b128 v[186:189], v143 offset:17408
	ds_read_b128 v[190:193], v143 offset:18432
	ds_read_b128 v[194:197], v143 offset:19456
	ds_read_b128 v[198:201], v143 offset:20480
	ds_read_b128 v[202:205], v143 offset:21504
	ds_read_b128 v[236:239], v143 offset:22528
	ds_read_b128 v[240:243], v143 offset:23552
	global_load_lds_dwordx4 v[168:169], off
	s_add_i32 m0, s29, 0x2000
	v_lshl_add_u64 v[206:207], s[36:37], 0, v[130:131]
	s_add_u32 s36, s36, s20
	s_addc_u32 s37, s37, 0
	s_add_i32 s28, s28, s41
	global_load_lds_dwordx4 v[206:207], off
	v_lshl_add_u64 v[228:229], s[36:37], 0, v[0:1]
	s_mov_b32 m0, s28
	v_lshl_add_u64 v[244:245], s[36:37], 0, v[130:131]
	global_load_lds_dwordx4 v[228:229], off
	s_add_i32 m0, s28, 0x2000
	v_lshl_add_u64 v[246:247], s[48:49], 0, v[134:135]
	global_load_lds_dwordx4 v[244:245], off
	s_mov_b32 m0, s54
	v_lshl_add_u64 v[248:249], s[48:49], 0, v[132:133]
	global_load_lds_dwordx4 v[246:247], off
	s_mov_b32 m0, s55
	s_nop 0
	global_load_lds_dwordx4 v[248:249], off
	s_waitcnt vmcnt(8)
	s_waitcnt lgkmcnt(0)
	s_barrier
	s_waitcnt lgkmcnt(0)
	v_mfma_f32_16x16x32_bf16 v[62:65], v[144:147], v[182:185], v[62:65]
	v_mfma_f32_16x16x32_bf16 v[58:61], v[152:155], v[182:185], v[58:61]
	v_mfma_f32_16x16x32_bf16 v[54:57], v[144:147], v[190:193], v[54:57]
	v_mfma_f32_16x16x32_bf16 v[50:53], v[152:155], v[190:193], v[50:53]
	v_mfma_f32_16x16x32_bf16 v[42:45], v[144:147], v[198:201], v[42:45]
	v_mfma_f32_16x16x32_bf16 v[34:37], v[152:155], v[198:201], v[34:37]
	v_mfma_f32_16x16x32_bf16 v[26:29], v[144:147], v[236:239], v[26:29]
	v_mfma_f32_16x16x32_bf16 v[18:21], v[152:155], v[236:239], v[18:21]
	v_mfma_f32_16x16x32_bf16 v[62:65], v[148:151], v[186:189], v[62:65]
	v_mfma_f32_16x16x32_bf16 v[58:61], v[156:159], v[186:189], v[58:61]
	v_mfma_f32_16x16x32_bf16 v[54:57], v[148:151], v[194:197], v[54:57]
	v_mfma_f32_16x16x32_bf16 v[50:53], v[156:159], v[194:197], v[50:53]
	v_mfma_f32_16x16x32_bf16 v[42:45], v[148:151], v[202:205], v[42:45]
	v_mfma_f32_16x16x32_bf16 v[34:37], v[156:159], v[202:205], v[34:37]
	v_mfma_f32_16x16x32_bf16 v[26:29], v[148:151], v[240:243], v[26:29]
	v_mfma_f32_16x16x32_bf16 v[18:21], v[156:159], v[240:243], v[18:21]
	v_mfma_f32_16x16x32_bf16 v[46:49], v[160:163], v[182:185], v[46:49]
	v_mfma_f32_16x16x32_bf16 v[38:41], v[174:177], v[182:185], v[38:41]
	v_mfma_f32_16x16x32_bf16 v[30:33], v[160:163], v[190:193], v[30:33]
	v_mfma_f32_16x16x32_bf16 v[22:25], v[174:177], v[190:193], v[22:25]
	v_mfma_f32_16x16x32_bf16 v[14:17], v[160:163], v[198:201], v[14:17]
	v_mfma_f32_16x16x32_bf16 v[10:13], v[174:177], v[198:201], v[10:13]
	v_mfma_f32_16x16x32_bf16 v[6:9], v[160:163], v[236:239], v[6:9]
	v_mfma_f32_16x16x32_bf16 v[2:5], v[174:177], v[236:239], v[2:5]
	v_mfma_f32_16x16x32_bf16 v[46:49], v[164:167], v[186:189], v[46:49]
	v_mfma_f32_16x16x32_bf16 v[38:41], v[178:181], v[186:189], v[38:41]
	v_mfma_f32_16x16x32_bf16 v[30:33], v[164:167], v[194:197], v[30:33]
	v_mfma_f32_16x16x32_bf16 v[22:25], v[178:181], v[194:197], v[22:25]
	v_mfma_f32_16x16x32_bf16 v[14:17], v[164:167], v[202:205], v[14:17]
	v_mfma_f32_16x16x32_bf16 v[10:13], v[178:181], v[202:205], v[10:13]
	v_mfma_f32_16x16x32_bf16 v[6:9], v[164:167], v[240:243], v[6:9]
	v_mfma_f32_16x16x32_bf16 v[2:5], v[178:181], v[240:243], v[2:5]
	s_barrier
	s_add_i32 s28, 0, 0x18000
	s_add_i32 s29, 0, 0x1c000
	v_add_u32_e32 v156, s28, v141
	v_add_u32_e32 v178, s29, v141
	ds_read_b128 v[144:147], v156
	ds_read_b128 v[148:151], v156 offset:1024
	ds_read_b128 v[152:155], v156 offset:2048
	ds_read_b128 v[156:159], v156 offset:3072
	ds_read_b128 v[160:163], v178
	ds_read_b128 v[164:167], v178 offset:1024
	ds_read_b128 v[174:177], v178 offset:2048
	ds_read_b128 v[178:181], v178 offset:3072
	s_add_u32 s36, s48, s20
	s_addc_u32 s37, s49, 0
	s_mov_b32 m0, s70
	v_lshl_add_u64 v[250:251], s[36:37], 0, v[134:135]
	ds_read_b128 v[182:185], v143 offset:32768
	ds_read_b128 v[186:189], v143 offset:33792
	ds_read_b128 v[190:193], v143 offset:34816
	ds_read_b128 v[194:197], v143 offset:35840
	ds_read_b128 v[198:201], v143 offset:36864
	ds_read_b128 v[202:205], v143 offset:37888
	ds_read_b128 v[236:239], v143 offset:38912
	ds_read_b128 v[240:243], v143 offset:39936
	global_load_lds_dwordx4 v[250:251], off
	v_lshl_add_u64 v[250:251], s[36:37], 0, v[132:133]
	s_mov_b32 m0, s71
	s_nop 0
	global_load_lds_dwordx4 v[250:251], off
	s_waitcnt vmcnt(8)
	s_waitcnt lgkmcnt(0)
	s_barrier
	s_waitcnt lgkmcnt(0)
	v_mfma_f32_16x16x32_bf16 v[126:129], v[144:147], v[182:185], v[126:129]
	v_mfma_f32_16x16x32_bf16 v[122:125], v[152:155], v[182:185], v[122:125]
	v_mfma_f32_16x16x32_bf16 v[118:121], v[144:147], v[190:193], v[118:121]
	v_mfma_f32_16x16x32_bf16 v[114:117], v[152:155], v[190:193], v[114:117]
	v_mfma_f32_16x16x32_bf16 v[106:109], v[144:147], v[198:201], v[106:109]
	v_mfma_f32_16x16x32_bf16 v[98:101], v[152:155], v[198:201], v[98:101]
	v_mfma_f32_16x16x32_bf16 v[90:93], v[144:147], v[236:239], v[90:93]
	v_mfma_f32_16x16x32_bf16 v[82:85], v[152:155], v[236:239], v[82:85]
	v_mfma_f32_16x16x32_bf16 v[126:129], v[148:151], v[186:189], v[126:129]
	v_mfma_f32_16x16x32_bf16 v[122:125], v[156:159], v[186:189], v[122:125]
	v_mfma_f32_16x16x32_bf16 v[118:121], v[148:151], v[194:197], v[118:121]
	v_mfma_f32_16x16x32_bf16 v[114:117], v[156:159], v[194:197], v[114:117]
	v_mfma_f32_16x16x32_bf16 v[106:109], v[148:151], v[202:205], v[106:109]
	v_mfma_f32_16x16x32_bf16 v[98:101], v[156:159], v[202:205], v[98:101]
	v_mfma_f32_16x16x32_bf16 v[90:93], v[148:151], v[240:243], v[90:93]
	v_mfma_f32_16x16x32_bf16 v[82:85], v[156:159], v[240:243], v[82:85]
	v_mfma_f32_16x16x32_bf16 v[110:113], v[160:163], v[182:185], v[110:113]
	v_mfma_f32_16x16x32_bf16 v[102:105], v[174:177], v[182:185], v[102:105]
	v_mfma_f32_16x16x32_bf16 v[94:97], v[160:163], v[190:193], v[94:97]
	v_mfma_f32_16x16x32_bf16 v[86:89], v[174:177], v[190:193], v[86:89]
	v_mfma_f32_16x16x32_bf16 v[78:81], v[160:163], v[198:201], v[78:81]
	v_mfma_f32_16x16x32_bf16 v[74:77], v[174:177], v[198:201], v[74:77]
	v_mfma_f32_16x16x32_bf16 v[70:73], v[160:163], v[236:239], v[70:73]
	v_mfma_f32_16x16x32_bf16 v[66:69], v[174:177], v[236:239], v[66:69]
	v_mfma_f32_16x16x32_bf16 v[110:113], v[164:167], v[186:189], v[110:113]
	v_mfma_f32_16x16x32_bf16 v[102:105], v[178:181], v[186:189], v[102:105]
	v_mfma_f32_16x16x32_bf16 v[94:97], v[164:167], v[194:197], v[94:97]
	v_mfma_f32_16x16x32_bf16 v[86:89], v[178:181], v[194:197], v[86:89]
	v_mfma_f32_16x16x32_bf16 v[78:81], v[164:167], v[202:205], v[78:81]
	v_mfma_f32_16x16x32_bf16 v[74:77], v[178:181], v[202:205], v[74:77]
	v_mfma_f32_16x16x32_bf16 v[70:73], v[164:167], v[240:243], v[70:73]
	v_mfma_f32_16x16x32_bf16 v[66:69], v[178:181], v[240:243], v[66:69]
	s_barrier
	s_add_i32 s28, s28, s41
	v_lshl_add_u64 v[168:169], v[168:169], 0, s[4:5]
	s_mov_b32 m0, s28
	ds_read_b128 v[182:185], v143 offset:49152
	ds_read_b128 v[186:189], v143 offset:50176
	ds_read_b128 v[190:193], v143 offset:51200
	ds_read_b128 v[194:197], v143 offset:52224
	ds_read_b128 v[198:201], v143 offset:53248
	ds_read_b128 v[202:205], v143 offset:54272
	ds_read_b128 v[236:239], v143 offset:55296
	ds_read_b128 v[240:243], v143 offset:56320
	global_load_lds_dwordx4 v[168:169], off
	v_lshl_add_u64 v[168:169], v[206:207], 0, s[4:5]
	s_add_i32 m0, s28, 0x2000
	s_add_i32 s28, s29, s41
	global_load_lds_dwordx4 v[168:169], off
	v_lshl_add_u64 v[168:169], v[228:229], 0, s[4:5]
	s_mov_b32 m0, s28
	s_nop 0
	global_load_lds_dwordx4 v[168:169], off
	v_lshl_add_u64 v[168:169], v[244:245], 0, s[4:5]
	s_add_i32 m0, s28, 0x2000
	s_nop 0
	global_load_lds_dwordx4 v[168:169], off
	v_lshl_add_u64 v[168:169], v[246:247], 0, s[4:5]
	s_mov_b32 m0, s83
	s_nop 0
	global_load_lds_dwordx4 v[168:169], off
	v_lshl_add_u64 v[168:169], v[248:249], 0, s[4:5]
	s_mov_b32 m0, s85
	s_nop 0
	global_load_lds_dwordx4 v[168:169], off
	s_waitcnt vmcnt(8)
	s_waitcnt lgkmcnt(0)
	s_barrier
	s_waitcnt lgkmcnt(0)
	v_mfma_f32_16x16x32_bf16 v[62:65], v[144:147], v[182:185], v[62:65]
	v_mfma_f32_16x16x32_bf16 v[58:61], v[152:155], v[182:185], v[58:61]
	v_mfma_f32_16x16x32_bf16 v[54:57], v[144:147], v[190:193], v[54:57]
	v_mfma_f32_16x16x32_bf16 v[50:53], v[152:155], v[190:193], v[50:53]
	v_mfma_f32_16x16x32_bf16 v[42:45], v[144:147], v[198:201], v[42:45]
	v_mfma_f32_16x16x32_bf16 v[34:37], v[152:155], v[198:201], v[34:37]
	v_mfma_f32_16x16x32_bf16 v[26:29], v[144:147], v[236:239], v[26:29]
	v_mfma_f32_16x16x32_bf16 v[18:21], v[152:155], v[236:239], v[18:21]
	v_mfma_f32_16x16x32_bf16 v[62:65], v[148:151], v[186:189], v[62:65]
	v_mfma_f32_16x16x32_bf16 v[58:61], v[156:159], v[186:189], v[58:61]
	v_mfma_f32_16x16x32_bf16 v[54:57], v[148:151], v[194:197], v[54:57]
	v_mfma_f32_16x16x32_bf16 v[50:53], v[156:159], v[194:197], v[50:53]
	v_mfma_f32_16x16x32_bf16 v[42:45], v[148:151], v[202:205], v[42:45]
	v_mfma_f32_16x16x32_bf16 v[34:37], v[156:159], v[202:205], v[34:37]
	v_mfma_f32_16x16x32_bf16 v[26:29], v[148:151], v[240:243], v[26:29]
	v_mfma_f32_16x16x32_bf16 v[18:21], v[156:159], v[240:243], v[18:21]
	v_mfma_f32_16x16x32_bf16 v[46:49], v[160:163], v[182:185], v[46:49]
	v_mfma_f32_16x16x32_bf16 v[38:41], v[174:177], v[182:185], v[38:41]
	v_mfma_f32_16x16x32_bf16 v[30:33], v[160:163], v[190:193], v[30:33]
	v_mfma_f32_16x16x32_bf16 v[22:25], v[174:177], v[190:193], v[22:25]
	v_mfma_f32_16x16x32_bf16 v[14:17], v[160:163], v[198:201], v[14:17]
	v_mfma_f32_16x16x32_bf16 v[10:13], v[174:177], v[198:201], v[10:13]
	v_mfma_f32_16x16x32_bf16 v[6:9], v[160:163], v[236:239], v[6:9]
	v_mfma_f32_16x16x32_bf16 v[2:5], v[174:177], v[236:239], v[2:5]
	v_mfma_f32_16x16x32_bf16 v[46:49], v[164:167], v[186:189], v[46:49]
	v_mfma_f32_16x16x32_bf16 v[38:41], v[178:181], v[186:189], v[38:41]
	v_mfma_f32_16x16x32_bf16 v[30:33], v[164:167], v[194:197], v[30:33]
	v_mfma_f32_16x16x32_bf16 v[22:25], v[178:181], v[194:197], v[22:25]
	v_mfma_f32_16x16x32_bf16 v[14:17], v[164:167], v[202:205], v[14:17]
	v_mfma_f32_16x16x32_bf16 v[10:13], v[178:181], v[202:205], v[10:13]
	v_mfma_f32_16x16x32_bf16 v[6:9], v[164:167], v[240:243], v[6:9]
	v_mfma_f32_16x16x32_bf16 v[2:5], v[178:181], v[240:243], v[2:5]
	s_barrier
	s_add_u32 s18, s18, 0x100
	s_addc_u32 s19, s19, 0
	s_add_u32 s11, s11, 0x100
	s_addc_u32 s15, s15, 0
	s_cmp_ge_u32 vcc_lo, s79
	s_mov_b32 s48, vcc_lo
	s_cbranch_scc0 .LBB0_219
	s_and_b64 vcc, exec, s[8:9]
	s_cbranch_vccz .LBB0_222
	s_barrier

.LBB0_437:
	s_add_u32 s12, s10, 0xfffc0080
	s_addc_u32 s13, s11, -1
	s_add_i32 s36, 0, 0x10000
	s_cmp_eq_u32 s78, 12
	s_cselect_b32 s15, s9, s13
	s_cselect_b32 s14, s45, s12
	s_cselect_b32 s13, s46, s77
	s_cselect_b32 s12, s47, s49
	s_add_i32 s37, 0, 0x14000
	v_add_u32_e32 v156, s36, v145
	v_add_u32_e32 v168, s37, v145
	ds_read_b128 v[140:143], v156
	ds_read_b128 v[148:151], v156 offset:1024
	ds_read_b128 v[152:155], v156 offset:2048
	ds_read_b128 v[156:159], v156 offset:3072
	ds_read_b128 v[160:163], v168
	ds_read_b128 v[164:167], v168 offset:1024
	ds_read_b128 v[174:177], v168 offset:2048
	ds_read_b128 v[178:181], v168 offset:3072
	v_lshl_add_u64 v[168:169], s[10:11], 0, v[136:137]
	s_add_i32 m0, s19, 0xc000
	ds_read_b128 v[182:185], v147
	ds_read_b128 v[186:189], v147 offset:1024
	ds_read_b128 v[190:193], v147 offset:2048
	ds_read_b128 v[194:197], v147 offset:3072
	ds_read_b128 v[198:201], v147 offset:4096
	ds_read_b128 v[202:205], v147 offset:5120
	ds_read_b128 v[236:239], v147 offset:6144
	ds_read_b128 v[240:243], v147 offset:7168
	global_load_lds_dwordx4 v[168:169], off
	v_lshl_add_u64 v[168:169], s[10:11], 0, v[138:139]
	s_add_i32 m0, s19, 0xe000
	s_nop 0
	global_load_lds_dwordx4 v[168:169], off
	s_waitcnt vmcnt(8)
	s_waitcnt lgkmcnt(0)
	s_barrier
	s_waitcnt lgkmcnt(0)
	v_mfma_f32_16x16x32_bf16 v[126:129], v[140:143], v[182:185], v[126:129]
	v_mfma_f32_16x16x32_bf16 v[122:125], v[152:155], v[182:185], v[122:125]
	v_mfma_f32_16x16x32_bf16 v[110:113], v[140:143], v[190:193], v[110:113]
	v_mfma_f32_16x16x32_bf16 v[106:109], v[152:155], v[190:193], v[106:109]
	v_mfma_f32_16x16x32_bf16 v[94:97], v[140:143], v[198:201], v[94:97]
	v_mfma_f32_16x16x32_bf16 v[90:93], v[152:155], v[198:201], v[90:93]
	v_mfma_f32_16x16x32_bf16 v[78:81], v[140:143], v[236:239], v[78:81]
	v_mfma_f32_16x16x32_bf16 v[74:77], v[152:155], v[236:239], v[74:77]
	v_mfma_f32_16x16x32_bf16 v[126:129], v[148:151], v[186:189], v[126:129]
	v_mfma_f32_16x16x32_bf16 v[122:125], v[156:159], v[186:189], v[122:125]
	v_mfma_f32_16x16x32_bf16 v[110:113], v[148:151], v[194:197], v[110:113]
	v_mfma_f32_16x16x32_bf16 v[106:109], v[156:159], v[194:197], v[106:109]
	v_mfma_f32_16x16x32_bf16 v[94:97], v[148:151], v[202:205], v[94:97]
	v_mfma_f32_16x16x32_bf16 v[90:93], v[156:159], v[202:205], v[90:93]
	v_mfma_f32_16x16x32_bf16 v[78:81], v[148:151], v[240:243], v[78:81]
	v_mfma_f32_16x16x32_bf16 v[74:77], v[156:159], v[240:243], v[74:77]
	v_mfma_f32_16x16x32_bf16 v[118:121], v[160:163], v[182:185], v[118:121]
	v_mfma_f32_16x16x32_bf16 v[114:117], v[174:177], v[182:185], v[114:117]
	v_mfma_f32_16x16x32_bf16 v[102:105], v[160:163], v[190:193], v[102:105]
	v_mfma_f32_16x16x32_bf16 v[98:101], v[174:177], v[190:193], v[98:101]
	v_mfma_f32_16x16x32_bf16 v[86:89], v[160:163], v[198:201], v[86:89]
	v_mfma_f32_16x16x32_bf16 v[82:85], v[174:177], v[198:201], v[82:85]
	v_mfma_f32_16x16x32_bf16 v[70:73], v[160:163], v[236:239], v[70:73]
	v_mfma_f32_16x16x32_bf16 v[66:69], v[174:177], v[236:239], v[66:69]
	v_mfma_f32_16x16x32_bf16 v[118:121], v[164:167], v[186:189], v[118:121]
	v_mfma_f32_16x16x32_bf16 v[114:117], v[178:181], v[186:189], v[114:117]
	v_mfma_f32_16x16x32_bf16 v[102:105], v[164:167], v[194:197], v[102:105]
	v_mfma_f32_16x16x32_bf16 v[98:101], v[178:181], v[194:197], v[98:101]
	v_mfma_f32_16x16x32_bf16 v[86:89], v[164:167], v[202:205], v[86:89]
	v_mfma_f32_16x16x32_bf16 v[82:85], v[178:181], v[202:205], v[82:85]
	v_mfma_f32_16x16x32_bf16 v[70:73], v[164:167], v[240:243], v[70:73]
	v_mfma_f32_16x16x32_bf16 v[66:69], v[178:181], v[240:243], v[66:69]
	s_barrier
	s_add_i32 s36, s36, s18
	v_lshl_add_u64 v[168:169], s[12:13], 0, v[0:1]
	s_mov_b32 m0, s36
	ds_read_b128 v[182:185], v147 offset:16384
	ds_read_b128 v[186:189], v147 offset:17408
	ds_read_b128 v[190:193], v147 offset:18432
	ds_read_b128 v[194:197], v147 offset:19456
	ds_read_b128 v[198:201], v147 offset:20480
	ds_read_b128 v[202:205], v147 offset:21504
	ds_read_b128 v[236:239], v147 offset:22528
	ds_read_b128 v[240:243], v147 offset:23552
	global_load_lds_dwordx4 v[168:169], off
	s_add_i32 m0, s36, 0x2000
	s_add_u32 s82, s12, 0x40000
	v_lshl_add_u64 v[206:207], s[12:13], 0, v[130:131]
	s_addc_u32 s83, s13, 0
	s_add_i32 s36, s37, s18
	global_load_lds_dwordx4 v[206:207], off
	v_lshl_add_u64 v[244:245], s[82:83], 0, v[0:1]
	s_mov_b32 m0, s36
	v_lshl_add_u64 v[246:247], s[14:15], 0, v[132:133]
	global_load_lds_dwordx4 v[244:245], off
	v_lshl_add_u64 v[244:245], s[82:83], 0, v[130:131]
	s_add_i32 m0, s36, 0x2000
	s_nop 0
	global_load_lds_dwordx4 v[244:245], off
	v_lshl_add_u64 v[244:245], s[14:15], 0, v[134:135]
	s_mov_b32 m0, s19
	s_nop 0
	global_load_lds_dwordx4 v[244:245], off
	s_mov_b32 m0, s34
	s_nop 0
	global_load_lds_dwordx4 v[246:247], off
	s_waitcnt vmcnt(8)
	s_waitcnt lgkmcnt(0)
	s_barrier
	s_waitcnt lgkmcnt(0)
	v_mfma_f32_16x16x32_bf16 v[62:65], v[140:143], v[182:185], v[62:65]
	v_mfma_f32_16x16x32_bf16 v[58:61], v[152:155], v[182:185], v[58:61]
	v_mfma_f32_16x16x32_bf16 v[46:49], v[140:143], v[190:193], v[46:49]
	v_mfma_f32_16x16x32_bf16 v[42:45], v[152:155], v[190:193], v[42:45]
	v_mfma_f32_16x16x32_bf16 v[30:33], v[140:143], v[198:201], v[30:33]
	v_mfma_f32_16x16x32_bf16 v[26:29], v[152:155], v[198:201], v[26:29]
	v_mfma_f32_16x16x32_bf16 v[14:17], v[140:143], v[236:239], v[14:17]
	v_mfma_f32_16x16x32_bf16 v[10:13], v[152:155], v[236:239], v[10:13]
	v_mfma_f32_16x16x32_bf16 v[62:65], v[148:151], v[186:189], v[62:65]
	v_mfma_f32_16x16x32_bf16 v[58:61], v[156:159], v[186:189], v[58:61]
	v_mfma_f32_16x16x32_bf16 v[46:49], v[148:151], v[194:197], v[46:49]
	v_mfma_f32_16x16x32_bf16 v[42:45], v[156:159], v[194:197], v[42:45]
	v_mfma_f32_16x16x32_bf16 v[30:33], v[148:151], v[202:205], v[30:33]
	v_mfma_f32_16x16x32_bf16 v[26:29], v[156:159], v[202:205], v[26:29]
	v_mfma_f32_16x16x32_bf16 v[14:17], v[148:151], v[240:243], v[14:17]
	v_mfma_f32_16x16x32_bf16 v[10:13], v[156:159], v[240:243], v[10:13]
	v_mfma_f32_16x16x32_bf16 v[54:57], v[160:163], v[182:185], v[54:57]
	v_mfma_f32_16x16x32_bf16 v[50:53], v[174:177], v[182:185], v[50:53]
	v_mfma_f32_16x16x32_bf16 v[38:41], v[160:163], v[190:193], v[38:41]
	v_mfma_f32_16x16x32_bf16 v[34:37], v[174:177], v[190:193], v[34:37]
	v_mfma_f32_16x16x32_bf16 v[22:25], v[160:163], v[198:201], v[22:25]
	v_mfma_f32_16x16x32_bf16 v[18:21], v[174:177], v[198:201], v[18:21]
	v_mfma_f32_16x16x32_bf16 v[6:9], v[160:163], v[236:239], v[6:9]
	v_mfma_f32_16x16x32_bf16 v[2:5], v[174:177], v[236:239], v[2:5]
	v_mfma_f32_16x16x32_bf16 v[54:57], v[164:167], v[186:189], v[54:57]
	v_mfma_f32_16x16x32_bf16 v[50:53], v[178:181], v[186:189], v[50:53]
	v_mfma_f32_16x16x32_bf16 v[38:41], v[164:167], v[194:197], v[38:41]
	v_mfma_f32_16x16x32_bf16 v[34:37], v[178:181], v[194:197], v[34:37]
	v_mfma_f32_16x16x32_bf16 v[22:25], v[164:167], v[202:205], v[22:25]
	v_mfma_f32_16x16x32_bf16 v[18:21], v[178:181], v[202:205], v[18:21]
	v_mfma_f32_16x16x32_bf16 v[6:9], v[164:167], v[240:243], v[6:9]
	v_mfma_f32_16x16x32_bf16 v[2:5], v[178:181], v[240:243], v[2:5]
	s_barrier
	s_add_i32 s36, 0, 0x18000
	s_add_i32 s37, 0, 0x1c000
	v_add_u32_e32 v156, s36, v145
	v_add_u32_e32 v178, s37, v145
	ds_read_b128 v[140:143], v156
	ds_read_b128 v[148:151], v156 offset:1024
	ds_read_b128 v[152:155], v156 offset:2048
	ds_read_b128 v[156:159], v156 offset:3072
	ds_read_b128 v[160:163], v178
	ds_read_b128 v[164:167], v178 offset:1024
	ds_read_b128 v[174:177], v178 offset:2048
	ds_read_b128 v[178:181], v178 offset:3072
	s_add_u32 s14, s14, 0x40000
	s_addc_u32 s15, s15, 0
	s_mov_b32 m0, s54
	v_lshl_add_u64 v[248:249], s[14:15], 0, v[134:135]
	ds_read_b128 v[182:185], v147 offset:32768
	ds_read_b128 v[186:189], v147 offset:33792
	ds_read_b128 v[190:193], v147 offset:34816
	ds_read_b128 v[194:197], v147 offset:35840
	ds_read_b128 v[198:201], v147 offset:36864
	ds_read_b128 v[202:205], v147 offset:37888
	ds_read_b128 v[236:239], v147 offset:38912
	ds_read_b128 v[240:243], v147 offset:39936
	global_load_lds_dwordx4 v[248:249], off
	v_lshl_add_u64 v[248:249], s[14:15], 0, v[132:133]
	s_mov_b32 m0, s55
	s_nop 0
	global_load_lds_dwordx4 v[248:249], off
	s_waitcnt vmcnt(8)
	s_waitcnt lgkmcnt(0)
	s_barrier
	s_waitcnt lgkmcnt(0)
	v_mfma_f32_16x16x32_bf16 v[126:129], v[140:143], v[182:185], v[126:129]
	v_mfma_f32_16x16x32_bf16 v[122:125], v[152:155], v[182:185], v[122:125]
	v_mfma_f32_16x16x32_bf16 v[110:113], v[140:143], v[190:193], v[110:113]
	v_mfma_f32_16x16x32_bf16 v[106:109], v[152:155], v[190:193], v[106:109]
	v_mfma_f32_16x16x32_bf16 v[94:97], v[140:143], v[198:201], v[94:97]
	v_mfma_f32_16x16x32_bf16 v[90:93], v[152:155], v[198:201], v[90:93]
	v_mfma_f32_16x16x32_bf16 v[78:81], v[140:143], v[236:239], v[78:81]
	v_mfma_f32_16x16x32_bf16 v[74:77], v[152:155], v[236:239], v[74:77]
	v_mfma_f32_16x16x32_bf16 v[126:129], v[148:151], v[186:189], v[126:129]
	v_mfma_f32_16x16x32_bf16 v[122:125], v[156:159], v[186:189], v[122:125]
	v_mfma_f32_16x16x32_bf16 v[110:113], v[148:151], v[194:197], v[110:113]
	v_mfma_f32_16x16x32_bf16 v[106:109], v[156:159], v[194:197], v[106:109]
	v_mfma_f32_16x16x32_bf16 v[94:97], v[148:151], v[202:205], v[94:97]
	v_mfma_f32_16x16x32_bf16 v[90:93], v[156:159], v[202:205], v[90:93]
	v_mfma_f32_16x16x32_bf16 v[78:81], v[148:151], v[240:243], v[78:81]
	v_mfma_f32_16x16x32_bf16 v[74:77], v[156:159], v[240:243], v[74:77]
	v_mfma_f32_16x16x32_bf16 v[118:121], v[160:163], v[182:185], v[118:121]
	v_mfma_f32_16x16x32_bf16 v[114:117], v[174:177], v[182:185], v[114:117]
	v_mfma_f32_16x16x32_bf16 v[102:105], v[160:163], v[190:193], v[102:105]
	v_mfma_f32_16x16x32_bf16 v[98:101], v[174:177], v[190:193], v[98:101]
	v_mfma_f32_16x16x32_bf16 v[86:89], v[160:163], v[198:201], v[86:89]
	v_mfma_f32_16x16x32_bf16 v[82:85], v[174:177], v[198:201], v[82:85]
	v_mfma_f32_16x16x32_bf16 v[70:73], v[160:163], v[236:239], v[70:73]
	v_mfma_f32_16x16x32_bf16 v[66:69], v[174:177], v[236:239], v[66:69]
	v_mfma_f32_16x16x32_bf16 v[118:121], v[164:167], v[186:189], v[118:121]
	v_mfma_f32_16x16x32_bf16 v[114:117], v[178:181], v[186:189], v[114:117]
	v_mfma_f32_16x16x32_bf16 v[102:105], v[164:167], v[194:197], v[102:105]
	v_mfma_f32_16x16x32_bf16 v[98:101], v[178:181], v[194:197], v[98:101]
	v_mfma_f32_16x16x32_bf16 v[86:89], v[164:167], v[202:205], v[86:89]
	v_mfma_f32_16x16x32_bf16 v[82:85], v[178:181], v[202:205], v[82:85]
	v_mfma_f32_16x16x32_bf16 v[70:73], v[164:167], v[240:243], v[70:73]
	v_mfma_f32_16x16x32_bf16 v[66:69], v[178:181], v[240:243], v[66:69]
	s_barrier
	s_add_i32 s14, s36, s18
	v_lshl_add_u64 v[168:169], v[168:169], 0, s[4:5]
	s_mov_b32 m0, s14
	ds_read_b128 v[182:185], v147 offset:49152
	ds_read_b128 v[186:189], v147 offset:50176
	ds_read_b128 v[190:193], v147 offset:51200
	ds_read_b128 v[194:197], v147 offset:52224
	ds_read_b128 v[198:201], v147 offset:53248
	ds_read_b128 v[202:205], v147 offset:54272
	ds_read_b128 v[236:239], v147 offset:55296
	ds_read_b128 v[240:243], v147 offset:56320
	global_load_lds_dwordx4 v[168:169], off
	s_add_i32 m0, s14, 0x2000
	s_add_u32 s12, s12, 0x40080
	v_lshl_add_u64 v[168:169], v[206:207], 0, s[4:5]
	s_addc_u32 s13, s13, 0
	s_add_i32 s14, s37, s18
	global_load_lds_dwordx4 v[168:169], off
	v_lshl_add_u64 v[168:169], s[12:13], 0, v[0:1]
	s_mov_b32 m0, s14
	s_nop 0
	global_load_lds_dwordx4 v[168:169], off
	v_lshl_add_u64 v[168:169], s[12:13], 0, v[130:131]
	s_add_i32 m0, s14, 0x2000
	s_nop 0
	global_load_lds_dwordx4 v[168:169], off
	v_lshl_add_u64 v[168:169], v[244:245], 0, s[4:5]
	s_mov_b32 m0, s70
	s_nop 0
	global_load_lds_dwordx4 v[168:169], off
	v_lshl_add_u64 v[168:169], v[246:247], 0, s[4:5]
	s_mov_b32 m0, s71
	s_nop 0
	global_load_lds_dwordx4 v[168:169], off
	s_waitcnt vmcnt(8)
	s_waitcnt lgkmcnt(0)
	s_barrier
	s_waitcnt lgkmcnt(0)
	v_mfma_f32_16x16x32_bf16 v[62:65], v[140:143], v[182:185], v[62:65]
	v_mfma_f32_16x16x32_bf16 v[58:61], v[152:155], v[182:185], v[58:61]
	v_mfma_f32_16x16x32_bf16 v[46:49], v[140:143], v[190:193], v[46:49]
	v_mfma_f32_16x16x32_bf16 v[42:45], v[152:155], v[190:193], v[42:45]
	v_mfma_f32_16x16x32_bf16 v[30:33], v[140:143], v[198:201], v[30:33]
	v_mfma_f32_16x16x32_bf16 v[26:29], v[152:155], v[198:201], v[26:29]
	v_mfma_f32_16x16x32_bf16 v[14:17], v[140:143], v[236:239], v[14:17]
	v_mfma_f32_16x16x32_bf16 v[10:13], v[152:155], v[236:239], v[10:13]
	v_mfma_f32_16x16x32_bf16 v[62:65], v[148:151], v[186:189], v[62:65]
	v_mfma_f32_16x16x32_bf16 v[58:61], v[156:159], v[186:189], v[58:61]
	v_mfma_f32_16x16x32_bf16 v[46:49], v[148:151], v[194:197], v[46:49]
	v_mfma_f32_16x16x32_bf16 v[42:45], v[156:159], v[194:197], v[42:45]
	v_mfma_f32_16x16x32_bf16 v[30:33], v[148:151], v[202:205], v[30:33]
	v_mfma_f32_16x16x32_bf16 v[26:29], v[156:159], v[202:205], v[26:29]
	v_mfma_f32_16x16x32_bf16 v[14:17], v[148:151], v[240:243], v[14:17]
	v_mfma_f32_16x16x32_bf16 v[10:13], v[156:159], v[240:243], v[10:13]
	v_mfma_f32_16x16x32_bf16 v[54:57], v[160:163], v[182:185], v[54:57]
	v_mfma_f32_16x16x32_bf16 v[50:53], v[174:177], v[182:185], v[50:53]
	v_mfma_f32_16x16x32_bf16 v[38:41], v[160:163], v[190:193], v[38:41]
	v_mfma_f32_16x16x32_bf16 v[34:37], v[174:177], v[190:193], v[34:37]
	v_mfma_f32_16x16x32_bf16 v[22:25], v[160:163], v[198:201], v[22:25]
	v_mfma_f32_16x16x32_bf16 v[18:21], v[174:177], v[198:201], v[18:21]
	v_mfma_f32_16x16x32_bf16 v[6:9], v[160:163], v[236:239], v[6:9]
	v_mfma_f32_16x16x32_bf16 v[2:5], v[174:177], v[236:239], v[2:5]
	v_mfma_f32_16x16x32_bf16 v[54:57], v[164:167], v[186:189], v[54:57]
	v_mfma_f32_16x16x32_bf16 v[50:53], v[178:181], v[186:189], v[50:53]
	v_mfma_f32_16x16x32_bf16 v[38:41], v[164:167], v[194:197], v[38:41]
	v_mfma_f32_16x16x32_bf16 v[34:37], v[178:181], v[194:197], v[34:37]
	v_mfma_f32_16x16x32_bf16 v[22:25], v[164:167], v[202:205], v[22:25]
	v_mfma_f32_16x16x32_bf16 v[18:21], v[178:181], v[202:205], v[18:21]
	v_mfma_f32_16x16x32_bf16 v[6:9], v[164:167], v[240:243], v[6:9]
	v_mfma_f32_16x16x32_bf16 v[2:5], v[178:181], v[240:243], v[2:5]
	s_barrier
	s_add_i32 s78, s78, 2
	s_add_u32 s10, s10, 0x100
	s_addc_u32 s11, s11, 0
	s_add_u32 s49, s49, 0x100
	s_addc_u32 s77, s77, 0
	s_cmp_gt_u32 s78, 13
	s_cbranch_scc0 .LBB0_437
	s_and_b64 vcc, exec, s[6:7]
	s_cbranch_vccz .LBB0_440
	s_barrier

.LBB0_493:
	s_add_u32 s16, s14, 0xfffc0080
	s_addc_u32 s17, s15, -1
	s_add_i32 s36, 0, 0x10000
	s_cmp_eq_u32 s46, 12
	s_cselect_b32 s19, s11, s17
	s_cselect_b32 s18, s13, s16
	s_cselect_b32 s17, s40, s45
	s_cselect_b32 s16, s41, s44
	s_add_i32 s37, 0, 0x14000
	v_add_u32_e32 v156, s36, v145
	v_add_u32_e32 v168, s37, v145
	ds_read_b128 v[140:143], v156
	ds_read_b128 v[148:151], v156 offset:1024
	ds_read_b128 v[152:155], v156 offset:2048
	ds_read_b128 v[156:159], v156 offset:3072
	ds_read_b128 v[160:163], v168
	ds_read_b128 v[164:167], v168 offset:1024
	ds_read_b128 v[174:177], v168 offset:2048
	ds_read_b128 v[178:181], v168 offset:3072
	v_lshl_add_u64 v[168:169], s[14:15], 0, v[136:137]
	s_add_i32 m0, s74, 0xc000
	ds_read_b128 v[182:185], v147
	ds_read_b128 v[186:189], v147 offset:1024
	ds_read_b128 v[190:193], v147 offset:2048
	ds_read_b128 v[194:197], v147 offset:3072
	ds_read_b128 v[198:201], v147 offset:4096
	ds_read_b128 v[202:205], v147 offset:5120
	ds_read_b128 v[236:239], v147 offset:6144
	ds_read_b128 v[240:243], v147 offset:7168
	global_load_lds_dwordx4 v[168:169], off
	v_lshl_add_u64 v[168:169], s[14:15], 0, v[138:139]
	s_add_i32 m0, s74, 0xe000
	s_nop 0
	global_load_lds_dwordx4 v[168:169], off
	s_waitcnt vmcnt(8)
	s_waitcnt lgkmcnt(0)
	s_barrier
	s_waitcnt lgkmcnt(0)
	v_mfma_f32_16x16x32_bf16 v[126:129], v[140:143], v[182:185], v[126:129]
	v_mfma_f32_16x16x32_bf16 v[122:125], v[152:155], v[182:185], v[122:125]
	v_mfma_f32_16x16x32_bf16 v[110:113], v[140:143], v[190:193], v[110:113]
	v_mfma_f32_16x16x32_bf16 v[106:109], v[152:155], v[190:193], v[106:109]
	v_mfma_f32_16x16x32_bf16 v[94:97], v[140:143], v[198:201], v[94:97]
	v_mfma_f32_16x16x32_bf16 v[90:93], v[152:155], v[198:201], v[90:93]
	v_mfma_f32_16x16x32_bf16 v[78:81], v[140:143], v[236:239], v[78:81]
	v_mfma_f32_16x16x32_bf16 v[74:77], v[152:155], v[236:239], v[74:77]
	v_mfma_f32_16x16x32_bf16 v[126:129], v[148:151], v[186:189], v[126:129]
	v_mfma_f32_16x16x32_bf16 v[122:125], v[156:159], v[186:189], v[122:125]
	v_mfma_f32_16x16x32_bf16 v[110:113], v[148:151], v[194:197], v[110:113]
	v_mfma_f32_16x16x32_bf16 v[106:109], v[156:159], v[194:197], v[106:109]
	v_mfma_f32_16x16x32_bf16 v[94:97], v[148:151], v[202:205], v[94:97]
	v_mfma_f32_16x16x32_bf16 v[90:93], v[156:159], v[202:205], v[90:93]
	v_mfma_f32_16x16x32_bf16 v[78:81], v[148:151], v[240:243], v[78:81]
	v_mfma_f32_16x16x32_bf16 v[74:77], v[156:159], v[240:243], v[74:77]
	v_mfma_f32_16x16x32_bf16 v[118:121], v[160:163], v[182:185], v[118:121]
	v_mfma_f32_16x16x32_bf16 v[114:117], v[174:177], v[182:185], v[114:117]
	v_mfma_f32_16x16x32_bf16 v[102:105], v[160:163], v[190:193], v[102:105]
	v_mfma_f32_16x16x32_bf16 v[98:101], v[174:177], v[190:193], v[98:101]
	v_mfma_f32_16x16x32_bf16 v[86:89], v[160:163], v[198:201], v[86:89]
	v_mfma_f32_16x16x32_bf16 v[82:85], v[174:177], v[198:201], v[82:85]
	v_mfma_f32_16x16x32_bf16 v[70:73], v[160:163], v[236:239], v[70:73]
	v_mfma_f32_16x16x32_bf16 v[66:69], v[174:177], v[236:239], v[66:69]
	v_mfma_f32_16x16x32_bf16 v[118:121], v[164:167], v[186:189], v[118:121]
	v_mfma_f32_16x16x32_bf16 v[114:117], v[178:181], v[186:189], v[114:117]
	v_mfma_f32_16x16x32_bf16 v[102:105], v[164:167], v[194:197], v[102:105]
	v_mfma_f32_16x16x32_bf16 v[98:101], v[178:181], v[194:197], v[98:101]
	v_mfma_f32_16x16x32_bf16 v[86:89], v[164:167], v[202:205], v[86:89]
	v_mfma_f32_16x16x32_bf16 v[82:85], v[178:181], v[202:205], v[82:85]
	v_mfma_f32_16x16x32_bf16 v[70:73], v[164:167], v[240:243], v[70:73]
	v_mfma_f32_16x16x32_bf16 v[66:69], v[178:181], v[240:243], v[66:69]
	s_barrier
	s_add_i32 s36, s36, s71
	v_lshl_add_u64 v[168:169], s[16:17], 0, v[0:1]
	s_mov_b32 m0, s36
	ds_read_b128 v[182:185], v147 offset:16384
	ds_read_b128 v[186:189], v147 offset:17408
	ds_read_b128 v[190:193], v147 offset:18432
	ds_read_b128 v[194:197], v147 offset:19456
	ds_read_b128 v[198:201], v147 offset:20480
	ds_read_b128 v[202:205], v147 offset:21504
	ds_read_b128 v[236:239], v147 offset:22528
	ds_read_b128 v[240:243], v147 offset:23552
	global_load_lds_dwordx4 v[168:169], off
	s_add_i32 m0, s36, 0x2000
	s_add_u32 s88, s16, 0x40000
	v_lshl_add_u64 v[206:207], s[16:17], 0, v[134:135]
	s_addc_u32 s89, s17, 0
	s_add_i32 s36, s37, s71
	global_load_lds_dwordx4 v[206:207], off
	v_lshl_add_u64 v[244:245], s[88:89], 0, v[0:1]
	s_mov_b32 m0, s36
	v_lshl_add_u64 v[246:247], s[18:19], 0, v[132:133]
	global_load_lds_dwordx4 v[244:245], off
	v_lshl_add_u64 v[244:245], s[88:89], 0, v[134:135]
	s_add_i32 m0, s36, 0x2000
	s_nop 0
	global_load_lds_dwordx4 v[244:245], off
	v_lshl_add_u64 v[244:245], s[18:19], 0, v[130:131]
	s_mov_b32 m0, s74
	s_nop 0
	global_load_lds_dwordx4 v[244:245], off
	s_mov_b32 m0, s75
	s_nop 0
	global_load_lds_dwordx4 v[246:247], off
	s_waitcnt vmcnt(8)
	s_waitcnt lgkmcnt(0)
	s_barrier
	s_waitcnt lgkmcnt(0)
	v_mfma_f32_16x16x32_bf16 v[62:65], v[140:143], v[182:185], v[62:65]
	v_mfma_f32_16x16x32_bf16 v[58:61], v[152:155], v[182:185], v[58:61]
	v_mfma_f32_16x16x32_bf16 v[46:49], v[140:143], v[190:193], v[46:49]
	v_mfma_f32_16x16x32_bf16 v[42:45], v[152:155], v[190:193], v[42:45]
	v_mfma_f32_16x16x32_bf16 v[30:33], v[140:143], v[198:201], v[30:33]
	v_mfma_f32_16x16x32_bf16 v[26:29], v[152:155], v[198:201], v[26:29]
	v_mfma_f32_16x16x32_bf16 v[14:17], v[140:143], v[236:239], v[14:17]
	v_mfma_f32_16x16x32_bf16 v[10:13], v[152:155], v[236:239], v[10:13]
	v_mfma_f32_16x16x32_bf16 v[62:65], v[148:151], v[186:189], v[62:65]
	v_mfma_f32_16x16x32_bf16 v[58:61], v[156:159], v[186:189], v[58:61]
	v_mfma_f32_16x16x32_bf16 v[46:49], v[148:151], v[194:197], v[46:49]
	v_mfma_f32_16x16x32_bf16 v[42:45], v[156:159], v[194:197], v[42:45]
	v_mfma_f32_16x16x32_bf16 v[30:33], v[148:151], v[202:205], v[30:33]
	v_mfma_f32_16x16x32_bf16 v[26:29], v[156:159], v[202:205], v[26:29]
	v_mfma_f32_16x16x32_bf16 v[14:17], v[148:151], v[240:243], v[14:17]
	v_mfma_f32_16x16x32_bf16 v[10:13], v[156:159], v[240:243], v[10:13]
	v_mfma_f32_16x16x32_bf16 v[54:57], v[160:163], v[182:185], v[54:57]
	v_mfma_f32_16x16x32_bf16 v[50:53], v[174:177], v[182:185], v[50:53]
	v_mfma_f32_16x16x32_bf16 v[38:41], v[160:163], v[190:193], v[38:41]
	v_mfma_f32_16x16x32_bf16 v[34:37], v[174:177], v[190:193], v[34:37]
	v_mfma_f32_16x16x32_bf16 v[22:25], v[160:163], v[198:201], v[22:25]
	v_mfma_f32_16x16x32_bf16 v[18:21], v[174:177], v[198:201], v[18:21]
	v_mfma_f32_16x16x32_bf16 v[6:9], v[160:163], v[236:239], v[6:9]
	v_mfma_f32_16x16x32_bf16 v[2:5], v[174:177], v[236:239], v[2:5]
	v_mfma_f32_16x16x32_bf16 v[54:57], v[164:167], v[186:189], v[54:57]
	v_mfma_f32_16x16x32_bf16 v[50:53], v[178:181], v[186:189], v[50:53]
	v_mfma_f32_16x16x32_bf16 v[38:41], v[164:167], v[194:197], v[38:41]
	v_mfma_f32_16x16x32_bf16 v[34:37], v[178:181], v[194:197], v[34:37]
	v_mfma_f32_16x16x32_bf16 v[22:25], v[164:167], v[202:205], v[22:25]
	v_mfma_f32_16x16x32_bf16 v[18:21], v[178:181], v[202:205], v[18:21]
	v_mfma_f32_16x16x32_bf16 v[6:9], v[164:167], v[240:243], v[6:9]
	v_mfma_f32_16x16x32_bf16 v[2:5], v[178:181], v[240:243], v[2:5]
	s_barrier
	s_add_i32 s36, 0, 0x18000
	s_add_i32 s37, 0, 0x1c000
	v_add_u32_e32 v156, s36, v145
	v_add_u32_e32 v178, s37, v145
	ds_read_b128 v[140:143], v156
	ds_read_b128 v[148:151], v156 offset:1024
	ds_read_b128 v[152:155], v156 offset:2048
	ds_read_b128 v[156:159], v156 offset:3072
	ds_read_b128 v[160:163], v178
	ds_read_b128 v[164:167], v178 offset:1024
	ds_read_b128 v[174:177], v178 offset:2048
	ds_read_b128 v[178:181], v178 offset:3072
	s_add_u32 s18, s18, 0x40000
	s_addc_u32 s19, s19, 0
	s_mov_b32 m0, s77
	v_lshl_add_u64 v[248:249], s[18:19], 0, v[130:131]
	ds_read_b128 v[182:185], v147 offset:32768
	ds_read_b128 v[186:189], v147 offset:33792
	ds_read_b128 v[190:193], v147 offset:34816
	ds_read_b128 v[194:197], v147 offset:35840
	ds_read_b128 v[198:201], v147 offset:36864
	ds_read_b128 v[202:205], v147 offset:37888
	ds_read_b128 v[236:239], v147 offset:38912
	ds_read_b128 v[240:243], v147 offset:39936
	global_load_lds_dwordx4 v[248:249], off
	v_lshl_add_u64 v[248:249], s[18:19], 0, v[132:133]
	s_mov_b32 m0, s78
	s_nop 0
	global_load_lds_dwordx4 v[248:249], off
	s_waitcnt vmcnt(8)
	s_waitcnt lgkmcnt(0)
	s_barrier
	s_waitcnt lgkmcnt(0)
	v_mfma_f32_16x16x32_bf16 v[126:129], v[140:143], v[182:185], v[126:129]
	v_mfma_f32_16x16x32_bf16 v[122:125], v[152:155], v[182:185], v[122:125]
	v_mfma_f32_16x16x32_bf16 v[110:113], v[140:143], v[190:193], v[110:113]
	v_mfma_f32_16x16x32_bf16 v[106:109], v[152:155], v[190:193], v[106:109]
	v_mfma_f32_16x16x32_bf16 v[94:97], v[140:143], v[198:201], v[94:97]
	v_mfma_f32_16x16x32_bf16 v[90:93], v[152:155], v[198:201], v[90:93]
	v_mfma_f32_16x16x32_bf16 v[78:81], v[140:143], v[236:239], v[78:81]
	v_mfma_f32_16x16x32_bf16 v[74:77], v[152:155], v[236:239], v[74:77]
	v_mfma_f32_16x16x32_bf16 v[126:129], v[148:151], v[186:189], v[126:129]
	v_mfma_f32_16x16x32_bf16 v[122:125], v[156:159], v[186:189], v[122:125]
	v_mfma_f32_16x16x32_bf16 v[110:113], v[148:151], v[194:197], v[110:113]
	v_mfma_f32_16x16x32_bf16 v[106:109], v[156:159], v[194:197], v[106:109]
	v_mfma_f32_16x16x32_bf16 v[94:97], v[148:151], v[202:205], v[94:97]
	v_mfma_f32_16x16x32_bf16 v[90:93], v[156:159], v[202:205], v[90:93]
	v_mfma_f32_16x16x32_bf16 v[78:81], v[148:151], v[240:243], v[78:81]
	v_mfma_f32_16x16x32_bf16 v[74:77], v[156:159], v[240:243], v[74:77]
	v_mfma_f32_16x16x32_bf16 v[118:121], v[160:163], v[182:185], v[118:121]
	v_mfma_f32_16x16x32_bf16 v[114:117], v[174:177], v[182:185], v[114:117]
	v_mfma_f32_16x16x32_bf16 v[102:105], v[160:163], v[190:193], v[102:105]
	v_mfma_f32_16x16x32_bf16 v[98:101], v[174:177], v[190:193], v[98:101]
	v_mfma_f32_16x16x32_bf16 v[86:89], v[160:163], v[198:201], v[86:89]
	v_mfma_f32_16x16x32_bf16 v[82:85], v[174:177], v[198:201], v[82:85]
	v_mfma_f32_16x16x32_bf16 v[70:73], v[160:163], v[236:239], v[70:73]
	v_mfma_f32_16x16x32_bf16 v[66:69], v[174:177], v[236:239], v[66:69]
	v_mfma_f32_16x16x32_bf16 v[118:121], v[164:167], v[186:189], v[118:121]
	v_mfma_f32_16x16x32_bf16 v[114:117], v[178:181], v[186:189], v[114:117]
	v_mfma_f32_16x16x32_bf16 v[102:105], v[164:167], v[194:197], v[102:105]
	v_mfma_f32_16x16x32_bf16 v[98:101], v[178:181], v[194:197], v[98:101]
	v_mfma_f32_16x16x32_bf16 v[86:89], v[164:167], v[202:205], v[86:89]
	v_mfma_f32_16x16x32_bf16 v[82:85], v[178:181], v[202:205], v[82:85]
	v_mfma_f32_16x16x32_bf16 v[70:73], v[164:167], v[240:243], v[70:73]
	v_mfma_f32_16x16x32_bf16 v[66:69], v[178:181], v[240:243], v[66:69]
	s_barrier
	s_add_i32 s18, s36, s71
	v_lshl_add_u64 v[168:169], v[168:169], 0, s[4:5]
	s_mov_b32 m0, s18
	ds_read_b128 v[182:185], v147 offset:49152
	ds_read_b128 v[186:189], v147 offset:50176
	ds_read_b128 v[190:193], v147 offset:51200
	ds_read_b128 v[194:197], v147 offset:52224
	ds_read_b128 v[198:201], v147 offset:53248
	ds_read_b128 v[202:205], v147 offset:54272
	ds_read_b128 v[236:239], v147 offset:55296
	ds_read_b128 v[240:243], v147 offset:56320
	global_load_lds_dwordx4 v[168:169], off
	s_add_i32 m0, s18, 0x2000
	s_add_u32 s16, s16, 0x40080
	v_lshl_add_u64 v[168:169], v[206:207], 0, s[4:5]
	s_addc_u32 s17, s17, 0
	s_add_i32 s18, s37, s71
	global_load_lds_dwordx4 v[168:169], off
	v_lshl_add_u64 v[168:169], s[16:17], 0, v[0:1]
	s_mov_b32 m0, s18
	s_nop 0
	global_load_lds_dwordx4 v[168:169], off
	v_lshl_add_u64 v[168:169], s[16:17], 0, v[134:135]
	s_add_i32 m0, s18, 0x2000
	s_nop 0
	global_load_lds_dwordx4 v[168:169], off
	v_lshl_add_u64 v[168:169], v[244:245], 0, s[4:5]
	s_mov_b32 m0, s79
	s_nop 0
	global_load_lds_dwordx4 v[168:169], off
	v_lshl_add_u64 v[168:169], v[246:247], 0, s[4:5]
	s_mov_b32 m0, s82
	s_nop 0
	global_load_lds_dwordx4 v[168:169], off
	s_waitcnt vmcnt(8)
	s_waitcnt lgkmcnt(0)
	s_barrier
	s_waitcnt lgkmcnt(0)
	v_mfma_f32_16x16x32_bf16 v[62:65], v[140:143], v[182:185], v[62:65]
	v_mfma_f32_16x16x32_bf16 v[58:61], v[152:155], v[182:185], v[58:61]
	v_mfma_f32_16x16x32_bf16 v[46:49], v[140:143], v[190:193], v[46:49]
	v_mfma_f32_16x16x32_bf16 v[42:45], v[152:155], v[190:193], v[42:45]
	v_mfma_f32_16x16x32_bf16 v[30:33], v[140:143], v[198:201], v[30:33]
	v_mfma_f32_16x16x32_bf16 v[26:29], v[152:155], v[198:201], v[26:29]
	v_mfma_f32_16x16x32_bf16 v[14:17], v[140:143], v[236:239], v[14:17]
	v_mfma_f32_16x16x32_bf16 v[10:13], v[152:155], v[236:239], v[10:13]
	v_mfma_f32_16x16x32_bf16 v[62:65], v[148:151], v[186:189], v[62:65]
	v_mfma_f32_16x16x32_bf16 v[58:61], v[156:159], v[186:189], v[58:61]
	v_mfma_f32_16x16x32_bf16 v[46:49], v[148:151], v[194:197], v[46:49]
	v_mfma_f32_16x16x32_bf16 v[42:45], v[156:159], v[194:197], v[42:45]
	v_mfma_f32_16x16x32_bf16 v[30:33], v[148:151], v[202:205], v[30:33]
	v_mfma_f32_16x16x32_bf16 v[26:29], v[156:159], v[202:205], v[26:29]
	v_mfma_f32_16x16x32_bf16 v[14:17], v[148:151], v[240:243], v[14:17]
	v_mfma_f32_16x16x32_bf16 v[10:13], v[156:159], v[240:243], v[10:13]
	v_mfma_f32_16x16x32_bf16 v[54:57], v[160:163], v[182:185], v[54:57]
	v_mfma_f32_16x16x32_bf16 v[50:53], v[174:177], v[182:185], v[50:53]
	v_mfma_f32_16x16x32_bf16 v[38:41], v[160:163], v[190:193], v[38:41]
	v_mfma_f32_16x16x32_bf16 v[34:37], v[174:177], v[190:193], v[34:37]
	v_mfma_f32_16x16x32_bf16 v[22:25], v[160:163], v[198:201], v[22:25]
	v_mfma_f32_16x16x32_bf16 v[18:21], v[174:177], v[198:201], v[18:21]
	v_mfma_f32_16x16x32_bf16 v[6:9], v[160:163], v[236:239], v[6:9]
	v_mfma_f32_16x16x32_bf16 v[2:5], v[174:177], v[236:239], v[2:5]
	v_mfma_f32_16x16x32_bf16 v[54:57], v[164:167], v[186:189], v[54:57]
	v_mfma_f32_16x16x32_bf16 v[50:53], v[178:181], v[186:189], v[50:53]
	v_mfma_f32_16x16x32_bf16 v[38:41], v[164:167], v[194:197], v[38:41]
	v_mfma_f32_16x16x32_bf16 v[34:37], v[178:181], v[194:197], v[34:37]
	v_mfma_f32_16x16x32_bf16 v[22:25], v[164:167], v[202:205], v[22:25]
	v_mfma_f32_16x16x32_bf16 v[18:21], v[178:181], v[202:205], v[18:21]
	v_mfma_f32_16x16x32_bf16 v[6:9], v[164:167], v[240:243], v[6:9]
	v_mfma_f32_16x16x32_bf16 v[2:5], v[178:181], v[240:243], v[2:5]
	s_barrier
	s_add_i32 s46, s46, 2
	s_add_u32 s14, s14, 0x100
	s_addc_u32 s15, s15, 0
	s_add_u32 s44, s44, 0x100
	s_addc_u32 s45, s45, 0
	s_cmp_gt_u32 s46, 13
	s_cbranch_scc0 .LBB0_493
	s_and_b64 vcc, exec, s[8:9]
	s_cbranch_vccz .LBB0_496
	s_barrier
